# DA unit epilogue hand-written: the two waves of a map pair each finish 64 of the 128 channels (symmetric exchange through LDS), same f32 math
# speedup vs baseline: 1.0641x; 1.0050x over previous
; __device__ void da_unit(char* lds, const Params& p, int layer, int unit) {
;     ...
;     u32x2 gwv[16];
;     if (c == 0) {
; #pragma unroll
;         for (int k = 0; k < 4; ++k)
; #pragma unroll
;             for (int g = 0; g < 4; ++g) gwv[k * 4 + g] = *(const u32x2*)(p.z + ZS_GATE + tokq * 1024 + h * 128 + 32 * k + 8 * g + 4 * h2);
;     }
;     const float lsum = lrow + __shfl_xor(lrow, 32);
;     float* xch = (float*)lds + qg * 4096;
;     if (c == 1) {
;         const float i1 = lam / lsum;
; #pragma unroll
;         for (int k = 0; k < 4; ++k)
; #pragma unroll
;             for (int e = 0; e < 16; ++e) xch[(k * 16 + e) * 64 + lane] = O[k][e] * i1;
;     }
.LBB0_525:
	s_or_b64 exec, exec, s[4:5]
	s_ashr_i32 s0, s6, 2
	s_ashr_i32 s1, s0, 31
	s_ashr_i32 s2, s7, 31
	s_lshl_b64 s[0:1], s[0:1], 11
	s_add_u32 s0, s0, s7
	s_addc_u32 s1, s1, s2
	s_cmp_eq_u32 s15, 0
	v_or_b32_e32 v64, s0, v147
	v_mov_b32_e32 v65, s1
	s_cselect_b64 s[0:1], -1, 0
	s_cmp_lg_u32 s15, 0
	s_cselect_b64 s[2:3], -1, 0
	s_and_b64 vcc, exec, s[2:3]
	v_lshlrev_b64 v[78:79], 11, v[64:65]
	v_mov_b32_e32 v253, v153
	s_lshl_b32 s70, s12, 8
	s_lshl_b32 s0, s15, 7
	s_add_i32 s70, s70, s0
	v_readlane_b32 s4, v254, 20
	v_readlane_b32 s5, v254, 21
	s_load_dword s2, s[86:87], 0xa0
	ds_bpermute_b32 v65, v244, v193
	s_nop 0
	v_lshl_add_u64 v[76:77], s[4:5], 0, v[78:79]
	v_lshl_add_u64 v[76:77], v[76:77], 0, s[70:71]
	v_lshl_add_u64 v[76:77], v[76:77], 0, v[252:253]
	global_load_dwordx2 v[200:201], v[76:77], off offset:0
	global_load_dwordx2 v[202:203], v[76:77], off offset:16
	global_load_dwordx2 v[204:205], v[76:77], off offset:32
	global_load_dwordx2 v[206:207], v[76:77], off offset:48
	global_load_dwordx2 v[208:209], v[76:77], off offset:64
	global_load_dwordx2 v[210:211], v[76:77], off offset:80
	global_load_dwordx2 v[212:213], v[76:77], off offset:96
	global_load_dwordx2 v[214:215], v[76:77], off offset:112
	v_lshl_add_u64 v[78:79], s[62:63], 0, v[78:79]
	v_lshl_add_u64 v[78:79], v[78:79], 0, s[70:71]
	v_lshl_add_u64 v[78:79], v[78:79], 0, v[252:253]
	s_lshl_b32 s4, s13, 14
	v_lshl_add_u32 v67, v184, 2, s4
	s_lshl_b32 s4, s13, 9
	s_lshl_b32 s5, s15, 8
	s_add_i32 s4, s4, s5
	s_add_i32 s4, s4, 0x10000
	v_lshl_add_u32 v68, v184, 2, s4
	s_waitcnt lgkmcnt(0)
	v_add_f32_e32 v65, v193, v65
	v_sub_f32_e32 v66, v191, v192
	v_subrev_f32_e32 v66, s2, v66
	s_cmp_eq_u32 s15, 0
	s_cselect_b64 s[0:1], -1, 0
	s_nop 0
	v_cndmask_b32_e64 v66, v66, 1.0, s[0:1]
	v_div_scale_f32 v72, s[0:1], v65, v65, v66
	v_div_scale_f32 v74, vcc, v66, v65, v66
	v_rcp_f32_e32 v73, v72
	s_nop 0
	v_fma_f32 v75, -v72, v73, 1.0
	v_fmac_f32_e32 v73, v75, v73
	v_mul_f32_e32 v75, v74, v73
	v_fma_f32 v64, -v72, v75, v74
	v_fmac_f32_e32 v75, v64, v73
	v_fma_f32 v72, -v72, v75, v74
	v_div_fmas_f32 v72, v72, v73, v75
	v_div_fixup_f32 v64, v72, v65, v66
	v_mul_f32_e32 v48, v48, v64
	v_mul_f32_e32 v49, v49, v64
	v_mul_f32_e32 v50, v50, v64
	v_mul_f32_e32 v51, v51, v64
	v_mul_f32_e32 v52, v52, v64
	v_mul_f32_e32 v53, v53, v64
	v_mul_f32_e32 v54, v54, v64
	v_mul_f32_e32 v55, v55, v64
	v_mul_f32_e32 v56, v56, v64
	v_mul_f32_e32 v57, v57, v64
	v_mul_f32_e32 v58, v58, v64
	v_mul_f32_e32 v59, v59, v64
	v_mul_f32_e32 v60, v60, v64
	v_mul_f32_e32 v61, v61, v64
	v_mul_f32_e32 v62, v62, v64
	v_mul_f32_e32 v63, v63, v64
	v_mul_f32_e32 v32, v32, v64
	v_mul_f32_e32 v33, v33, v64
	v_mul_f32_e32 v34, v34, v64
	v_mul_f32_e32 v35, v35, v64
	v_mul_f32_e32 v36, v36, v64
	v_mul_f32_e32 v37, v37, v64
	v_mul_f32_e32 v38, v38, v64
	v_mul_f32_e32 v39, v39, v64
	v_mul_f32_e32 v40, v40, v64
	v_mul_f32_e32 v41, v41, v64
	v_mul_f32_e32 v42, v42, v64
	v_mul_f32_e32 v43, v43, v64
	v_mul_f32_e32 v44, v44, v64
	v_mul_f32_e32 v45, v45, v64
	v_mul_f32_e32 v46, v46, v64
	v_mul_f32_e32 v47, v47, v64
	v_mul_f32_e32 v16, v16, v64
	v_mul_f32_e32 v17, v17, v64
	v_mul_f32_e32 v18, v18, v64
	v_mul_f32_e32 v19, v19, v64
	v_mul_f32_e32 v20, v20, v64
	v_mul_f32_e32 v21, v21, v64
	v_mul_f32_e32 v22, v22, v64
	v_mul_f32_e32 v23, v23, v64
	v_mul_f32_e32 v24, v24, v64
	v_mul_f32_e32 v25, v25, v64
	v_mul_f32_e32 v26, v26, v64
	v_mul_f32_e32 v27, v27, v64
	v_mul_f32_e32 v28, v28, v64
	v_mul_f32_e32 v29, v29, v64
	v_mul_f32_e32 v30, v30, v64
	v_mul_f32_e32 v31, v31, v64
	v_mul_f32_e32 v0, v0, v64
	v_mul_f32_e32 v1, v1, v64
	v_mul_f32_e32 v2, v2, v64
	v_mul_f32_e32 v3, v3, v64
	v_mul_f32_e32 v4, v4, v64
	v_mul_f32_e32 v5, v5, v64
	v_mul_f32_e32 v6, v6, v64
	v_mul_f32_e32 v7, v7, v64
	v_mul_f32_e32 v8, v8, v64
	v_mul_f32_e32 v9, v9, v64
	v_mul_f32_e32 v10, v10, v64
	v_mul_f32_e32 v11, v11, v64
	v_mul_f32_e32 v12, v12, v64
	v_mul_f32_e32 v13, v13, v64
	v_mul_f32_e32 v14, v14, v64
	v_mul_f32_e32 v15, v15, v64
	s_cmp_lg_u32 s15, 0
	s_cbranch_scc1 .Ldt_c1
	ds_write2st64_b32 v67, v16, v17 offset0:32 offset1:33
	ds_write2st64_b32 v67, v18, v19 offset0:34 offset1:35
	ds_write2st64_b32 v67, v20, v21 offset0:36 offset1:37
	ds_write2st64_b32 v67, v22, v23 offset0:38 offset1:39
	ds_write2st64_b32 v67, v24, v25 offset0:40 offset1:41
	ds_write2st64_b32 v67, v26, v27 offset0:42 offset1:43
	ds_write2st64_b32 v67, v28, v29 offset0:44 offset1:45
	ds_write2st64_b32 v67, v30, v31 offset0:46 offset1:47
	ds_write2st64_b32 v67, v0, v1 offset0:48 offset1:49
	ds_write2st64_b32 v67, v2, v3 offset0:50 offset1:51
	ds_write2st64_b32 v67, v4, v5 offset0:52 offset1:53
	ds_write2st64_b32 v67, v6, v7 offset0:54 offset1:55
	ds_write2st64_b32 v67, v8, v9 offset0:56 offset1:57
	ds_write2st64_b32 v67, v10, v11 offset0:58 offset1:59
	ds_write2st64_b32 v67, v12, v13 offset0:60 offset1:61
	ds_write2st64_b32 v67, v14, v15 offset0:62 offset1:63
	s_waitcnt lgkmcnt(0)
	s_barrier
; __device__ __forceinline__ float bflo(unsigned w) { return __uint_as_float(w << 16); }
; __device__ __forceinline__ float bfhi(unsigned w) { return __uint_as_float(w & 0xffff0000u); }
; __device__ __forceinline__ float silu_f(float x) { return x / (1.0f + __expf(-x)); }
; __device__ void da_unit(char* lds, const Params& p, int layer, int unit) {
;     ...
;     if (c == 0) {
;         const float i0 = 1.0f / lsum;
;         float ss = 0.f;
; #pragma unroll
;         for (int k = 0; k < 4; ++k)
; #pragma unroll
;             for (int e = 0; e < 16; ++e) { const float a = O[k][e] * i0 - xch[(k * 16 + e) * 64 + lane]; O[k][e] = a; ss += a * a; }
;         ss += __shfl_xor(ss, 32);
;         const float rstd = rsqrtf(ss * (1.0f / 128.0f) + RMS_EPS) * (1.0f - p.lam_init[layer]);
;         const float* sg = (const float*)(lds + LDS_SG_OFF);
;         __builtin_amdgcn_sched_barrier(0);
; #pragma unroll
;         for (int k = 0; k < 4; ++k)
; #pragma unroll
;             for (int g = 0; g < 4; ++g) {
;                 const int d0 = 32 * k + 8 * g + 4 * h2;
;                 const f32x4 gg = *(const f32x4*)(sg + d0);
;                 const u32x2 gw = gwv[k * 4 + g];
;                 const float o0 = O[k][4 * g + 0] * rstd * gg[0] * silu_f(bflo(gw.x));
;                 const float o1 = O[k][4 * g + 1] * rstd * gg[1] * silu_f(bfhi(gw.x));
;                 const float o2 = O[k][4 * g + 2] * rstd * gg[2] * silu_f(bflo(gw.y));
;                 const float o3 = O[k][4 * g + 3] * rstd * gg[3] * silu_f(bfhi(gw.y));
	ds_read2st64_b32 v[80:81], v67 offset0:0 offset1:1
	ds_read2st64_b32 v[82:83], v67 offset0:2 offset1:3
	ds_read2st64_b32 v[84:85], v67 offset0:4 offset1:5
	ds_read2st64_b32 v[86:87], v67 offset0:6 offset1:7
	ds_read2st64_b32 v[88:89], v67 offset0:8 offset1:9
	ds_read2st64_b32 v[90:91], v67 offset0:10 offset1:11
	ds_read2st64_b32 v[92:93], v67 offset0:12 offset1:13
	ds_read2st64_b32 v[94:95], v67 offset0:14 offset1:15
	s_waitcnt lgkmcnt(0)
	v_add_f32_e32 v48, v48, v80
	v_add_f32_e32 v49, v49, v81
	v_add_f32_e32 v50, v50, v82
	v_add_f32_e32 v51, v51, v83
	v_add_f32_e32 v52, v52, v84
	v_add_f32_e32 v53, v53, v85
	v_add_f32_e32 v54, v54, v86
	v_add_f32_e32 v55, v55, v87
	v_add_f32_e32 v56, v56, v88
	v_add_f32_e32 v57, v57, v89
	v_add_f32_e32 v58, v58, v90
	v_add_f32_e32 v59, v59, v91
	v_add_f32_e32 v60, v60, v92
	v_add_f32_e32 v61, v61, v93
	v_add_f32_e32 v62, v62, v94
	v_add_f32_e32 v63, v63, v95
	v_mul_f32_e32 v69, v48, v48
	v_fmac_f32_e32 v69, v49, v49
	v_fmac_f32_e32 v69, v50, v50
	v_fmac_f32_e32 v69, v51, v51
	v_fmac_f32_e32 v69, v52, v52
	v_fmac_f32_e32 v69, v53, v53
	v_fmac_f32_e32 v69, v54, v54
	v_fmac_f32_e32 v69, v55, v55
	v_fmac_f32_e32 v69, v56, v56
	v_fmac_f32_e32 v69, v57, v57
	v_fmac_f32_e32 v69, v58, v58
	v_fmac_f32_e32 v69, v59, v59
	v_fmac_f32_e32 v69, v60, v60
	v_fmac_f32_e32 v69, v61, v61
	v_fmac_f32_e32 v69, v62, v62
	v_fmac_f32_e32 v69, v63, v63
	ds_read2st64_b32 v[80:81], v67 offset0:16 offset1:17
	ds_read2st64_b32 v[82:83], v67 offset0:18 offset1:19
	ds_read2st64_b32 v[84:85], v67 offset0:20 offset1:21
	ds_read2st64_b32 v[86:87], v67 offset0:22 offset1:23
	ds_read2st64_b32 v[88:89], v67 offset0:24 offset1:25
	ds_read2st64_b32 v[90:91], v67 offset0:26 offset1:27
	ds_read2st64_b32 v[92:93], v67 offset0:28 offset1:29
	ds_read2st64_b32 v[94:95], v67 offset0:30 offset1:31
	s_waitcnt lgkmcnt(0)
	v_add_f32_e32 v32, v32, v80
	v_add_f32_e32 v33, v33, v81
	v_add_f32_e32 v34, v34, v82
	v_add_f32_e32 v35, v35, v83
	v_add_f32_e32 v36, v36, v84
	v_add_f32_e32 v37, v37, v85
	v_add_f32_e32 v38, v38, v86
	v_add_f32_e32 v39, v39, v87
	v_add_f32_e32 v40, v40, v88
	v_add_f32_e32 v41, v41, v89
	v_add_f32_e32 v42, v42, v90
	v_add_f32_e32 v43, v43, v91
	v_add_f32_e32 v44, v44, v92
	v_add_f32_e32 v45, v45, v93
	v_add_f32_e32 v46, v46, v94
	v_add_f32_e32 v47, v47, v95
	v_fmac_f32_e32 v69, v32, v32
	v_fmac_f32_e32 v69, v33, v33
	v_fmac_f32_e32 v69, v34, v34
	v_fmac_f32_e32 v69, v35, v35
	v_fmac_f32_e32 v69, v36, v36
	v_fmac_f32_e32 v69, v37, v37
	v_fmac_f32_e32 v69, v38, v38
	v_fmac_f32_e32 v69, v39, v39
	v_fmac_f32_e32 v69, v40, v40
	v_fmac_f32_e32 v69, v41, v41
	v_fmac_f32_e32 v69, v42, v42
	v_fmac_f32_e32 v69, v43, v43
	v_fmac_f32_e32 v69, v44, v44
	v_fmac_f32_e32 v69, v45, v45
	v_fmac_f32_e32 v69, v46, v46
	v_fmac_f32_e32 v69, v47, v47
	ds_bpermute_b32 v72, v244, v69
	s_waitcnt lgkmcnt(0)
	v_add_f32_e32 v69, v69, v72
	ds_write_b32 v68, v69
	s_waitcnt lgkmcnt(0)
	s_barrier
	ds_read_b32 v72, v68 offset:256
	v_mov_b32_e32 v74, 0x358637bd
	v_sub_f32_e64 v75, 1.0, s2
	s_waitcnt lgkmcnt(0)
	v_add_f32_e32 v69, v69, v72
	v_fmamk_f32 v69, v69, 0x3c000000, v74
	v_rsq_f32_e32 v69, v69
	s_nop 0
	v_mul_f32_e32 v70, v75, v69
	v_lshl_add_u32 v72, v188, 4, 0
	v_add_u32_e32 v72, 0x26b30, v72
	s_waitcnt vmcnt(0)
	ds_read_b128 v[216:219], v72 offset:0
	v_lshlrev_b32_e32 v96, 16, v200
	v_and_b32_e32 v97, 0xffff0000, v200
	v_lshlrev_b32_e32 v98, 16, v201
	v_and_b32_e32 v99, 0xffff0000, v201
	v_mul_f32_e32 v104, 0xbfb8aa3b, v96
	v_mul_f32_e32 v105, 0xbfb8aa3b, v97
	v_mul_f32_e32 v106, 0xbfb8aa3b, v98
	v_mul_f32_e32 v107, 0xbfb8aa3b, v99
	v_exp_f32_e32 v104, v104
	v_exp_f32_e32 v105, v105
	v_exp_f32_e32 v106, v106
	v_exp_f32_e32 v107, v107
	v_add_f32_e32 v104, 1.0, v104
	v_add_f32_e32 v105, 1.0, v105
	v_add_f32_e32 v106, 1.0, v106
	v_add_f32_e32 v107, 1.0, v107
	v_div_scale_f32 v108, s[0:1], v104, v104, v96
	v_div_scale_f32 v109, s[0:1], v105, v105, v97
	v_div_scale_f32 v110, s[0:1], v106, v106, v98
	v_div_scale_f32 v111, s[0:1], v107, v107, v99
	v_rcp_f32_e32 v112, v108
	v_rcp_f32_e32 v113, v109
	v_rcp_f32_e32 v114, v110
	v_rcp_f32_e32 v115, v111
	v_fma_f32 v100, -v108, v112, 1.0
	v_fma_f32 v101, -v109, v113, 1.0
	v_fma_f32 v102, -v110, v114, 1.0
	v_fma_f32 v103, -v111, v115, 1.0
	v_fmac_f32_e32 v112, v100, v112
	v_fmac_f32_e32 v113, v101, v113
	v_fmac_f32_e32 v114, v102, v114
	v_fmac_f32_e32 v115, v103, v115
	v_div_scale_f32 v116, vcc, v96, v104, v96
	v_mul_f32_e32 v100, v116, v112
	v_fma_f32 v120, -v108, v100, v116
	v_fmac_f32_e32 v100, v120, v112
	v_fma_f32 v120, -v108, v100, v116
	v_div_fmas_f32 v120, v120, v112, v100
	v_div_fixup_f32 v100, v120, v104, v96
	v_div_scale_f32 v117, vcc, v97, v105, v97
	v_mul_f32_e32 v101, v117, v113
	v_fma_f32 v120, -v109, v101, v117
	v_fmac_f32_e32 v101, v120, v113
	v_fma_f32 v120, -v109, v101, v117
	v_div_fmas_f32 v120, v120, v113, v101
	v_div_fixup_f32 v101, v120, v105, v97
	v_div_scale_f32 v118, vcc, v98, v106, v98
	v_mul_f32_e32 v102, v118, v114
	v_fma_f32 v120, -v110, v102, v118
	v_fmac_f32_e32 v102, v120, v114
	v_fma_f32 v120, -v110, v102, v118
	v_div_fmas_f32 v120, v120, v114, v102
	v_div_fixup_f32 v102, v120, v106, v98
	v_div_scale_f32 v119, vcc, v99, v107, v99
	v_mul_f32_e32 v103, v119, v115
	v_fma_f32 v120, -v111, v103, v119
	v_fmac_f32_e32 v103, v120, v115
	v_fma_f32 v120, -v111, v103, v119
	v_div_fmas_f32 v120, v120, v115, v103
	v_div_fixup_f32 v103, v120, v107, v99
	s_waitcnt lgkmcnt(0)
; __device__ __forceinline__ float bflo(unsigned w) { return __uint_as_float(w << 16); }
; __device__ __forceinline__ float bfhi(unsigned w) { return __uint_as_float(w & 0xffff0000u); }
; __device__ __forceinline__ float silu_f(float x) { return x / (1.0f + __expf(-x)); }
; __device__ void da_unit(char* lds, const Params& p, int layer, int unit) {
;     ...
; #pragma unroll
;         for (int k = 0; k < 4; ++k)
; #pragma unroll
;             for (int g = 0; g < 4; ++g) {
;                 const int d0 = 32 * k + 8 * g + 4 * h2;
;                 const f32x4 gg = *(const f32x4*)(sg + d0);
;                 const u32x2 gw = gwv[k * 4 + g];
;                 const float o0 = O[k][4 * g + 0] * rstd * gg[0] * silu_f(bflo(gw.x));
;                 const float o1 = O[k][4 * g + 1] * rstd * gg[1] * silu_f(bfhi(gw.x));
;                 const float o2 = O[k][4 * g + 2] * rstd * gg[2] * silu_f(bflo(gw.y));
;                 const float o3 = O[k][4 * g + 3] * rstd * gg[3] * silu_f(bfhi(gw.y));
;                 u32x2 w; w.x = cvt_pk_bf16(o0, o1); w.y = cvt_pk_bf16(o2, o3);
;                 *(u32x2*)(p.o + tokq * 1024 + h * 128 + d0) = w;
;             }
	v_mul_f32_e32 v48, v48, v70
	v_mul_f32_e32 v48, v48, v216
	v_mul_f32_e32 v48, v48, v100
	v_mul_f32_e32 v49, v49, v70
	v_mul_f32_e32 v49, v49, v217
	v_mul_f32_e32 v49, v49, v101
	v_mul_f32_e32 v50, v50, v70
	v_mul_f32_e32 v50, v50, v218
	v_mul_f32_e32 v50, v50, v102
	v_mul_f32_e32 v51, v51, v70
	v_mul_f32_e32 v51, v51, v219
	v_mul_f32_e32 v51, v51, v103
	v_cvt_pk_bf16_f32 v96, v48, v49
	v_cvt_pk_bf16_f32 v97, v50, v51
	global_store_dwordx2 v[78:79], v[96:97], off offset:0
	ds_read_b128 v[216:219], v72 offset:32
	v_lshlrev_b32_e32 v96, 16, v202
	v_and_b32_e32 v97, 0xffff0000, v202
	v_lshlrev_b32_e32 v98, 16, v203
	v_and_b32_e32 v99, 0xffff0000, v203
	v_mul_f32_e32 v104, 0xbfb8aa3b, v96
	v_mul_f32_e32 v105, 0xbfb8aa3b, v97
	v_mul_f32_e32 v106, 0xbfb8aa3b, v98
	v_mul_f32_e32 v107, 0xbfb8aa3b, v99
	v_exp_f32_e32 v104, v104
	v_exp_f32_e32 v105, v105
	v_exp_f32_e32 v106, v106
	v_exp_f32_e32 v107, v107
	v_add_f32_e32 v104, 1.0, v104
	v_add_f32_e32 v105, 1.0, v105
	v_add_f32_e32 v106, 1.0, v106
	v_add_f32_e32 v107, 1.0, v107
	v_div_scale_f32 v108, s[0:1], v104, v104, v96
	v_div_scale_f32 v109, s[0:1], v105, v105, v97
	v_div_scale_f32 v110, s[0:1], v106, v106, v98
	v_div_scale_f32 v111, s[0:1], v107, v107, v99
	v_rcp_f32_e32 v112, v108
	v_rcp_f32_e32 v113, v109
	v_rcp_f32_e32 v114, v110
	v_rcp_f32_e32 v115, v111
	v_fma_f32 v100, -v108, v112, 1.0
	v_fma_f32 v101, -v109, v113, 1.0
	v_fma_f32 v102, -v110, v114, 1.0
	v_fma_f32 v103, -v111, v115, 1.0
	v_fmac_f32_e32 v112, v100, v112
	v_fmac_f32_e32 v113, v101, v113
	v_fmac_f32_e32 v114, v102, v114
	v_fmac_f32_e32 v115, v103, v115
	v_div_scale_f32 v116, vcc, v96, v104, v96
	v_mul_f32_e32 v100, v116, v112
	v_fma_f32 v120, -v108, v100, v116
	v_fmac_f32_e32 v100, v120, v112
	v_fma_f32 v120, -v108, v100, v116
	v_div_fmas_f32 v120, v120, v112, v100
	v_div_fixup_f32 v100, v120, v104, v96
	v_div_scale_f32 v117, vcc, v97, v105, v97
	v_mul_f32_e32 v101, v117, v113
	v_fma_f32 v120, -v109, v101, v117
	v_fmac_f32_e32 v101, v120, v113
	v_fma_f32 v120, -v109, v101, v117
	v_div_fmas_f32 v120, v120, v113, v101
	v_div_fixup_f32 v101, v120, v105, v97
	v_div_scale_f32 v118, vcc, v98, v106, v98
	v_mul_f32_e32 v102, v118, v114
	v_fma_f32 v120, -v110, v102, v118
	v_fmac_f32_e32 v102, v120, v114
	v_fma_f32 v120, -v110, v102, v118
	v_div_fmas_f32 v120, v120, v114, v102
	v_div_fixup_f32 v102, v120, v106, v98
	v_div_scale_f32 v119, vcc, v99, v107, v99
	v_mul_f32_e32 v103, v119, v115
	v_fma_f32 v120, -v111, v103, v119
	v_fmac_f32_e32 v103, v120, v115
	v_fma_f32 v120, -v111, v103, v119
	v_div_fmas_f32 v120, v120, v115, v103
	v_div_fixup_f32 v103, v120, v107, v99
	s_waitcnt lgkmcnt(0)
	v_mul_f32_e32 v52, v52, v70
	v_mul_f32_e32 v52, v52, v216
	v_mul_f32_e32 v52, v52, v100
	v_mul_f32_e32 v53, v53, v70
	v_mul_f32_e32 v53, v53, v217
	v_mul_f32_e32 v53, v53, v101
	v_mul_f32_e32 v54, v54, v70
	v_mul_f32_e32 v54, v54, v218
	v_mul_f32_e32 v54, v54, v102
	v_mul_f32_e32 v55, v55, v70
	v_mul_f32_e32 v55, v55, v219
	v_mul_f32_e32 v55, v55, v103
	v_cvt_pk_bf16_f32 v96, v52, v53
	v_cvt_pk_bf16_f32 v97, v54, v55
	global_store_dwordx2 v[78:79], v[96:97], off offset:16
	ds_read_b128 v[216:219], v72 offset:64
	v_lshlrev_b32_e32 v96, 16, v204
	v_and_b32_e32 v97, 0xffff0000, v204
	v_lshlrev_b32_e32 v98, 16, v205
	v_and_b32_e32 v99, 0xffff0000, v205
	v_mul_f32_e32 v104, 0xbfb8aa3b, v96
	v_mul_f32_e32 v105, 0xbfb8aa3b, v97
	v_mul_f32_e32 v106, 0xbfb8aa3b, v98
	v_mul_f32_e32 v107, 0xbfb8aa3b, v99
	v_exp_f32_e32 v104, v104
	v_exp_f32_e32 v105, v105
	v_exp_f32_e32 v106, v106
	v_exp_f32_e32 v107, v107
	v_add_f32_e32 v104, 1.0, v104
	v_add_f32_e32 v105, 1.0, v105
	v_add_f32_e32 v106, 1.0, v106
	v_add_f32_e32 v107, 1.0, v107
	v_div_scale_f32 v108, s[0:1], v104, v104, v96
	v_div_scale_f32 v109, s[0:1], v105, v105, v97
	v_div_scale_f32 v110, s[0:1], v106, v106, v98
	v_div_scale_f32 v111, s[0:1], v107, v107, v99
	v_rcp_f32_e32 v112, v108
	v_rcp_f32_e32 v113, v109
	v_rcp_f32_e32 v114, v110
	v_rcp_f32_e32 v115, v111
	v_fma_f32 v100, -v108, v112, 1.0
	v_fma_f32 v101, -v109, v113, 1.0
	v_fma_f32 v102, -v110, v114, 1.0
	v_fma_f32 v103, -v111, v115, 1.0
	v_fmac_f32_e32 v112, v100, v112
	v_fmac_f32_e32 v113, v101, v113
	v_fmac_f32_e32 v114, v102, v114
	v_fmac_f32_e32 v115, v103, v115
	v_div_scale_f32 v116, vcc, v96, v104, v96
	v_mul_f32_e32 v100, v116, v112
	v_fma_f32 v120, -v108, v100, v116
	v_fmac_f32_e32 v100, v120, v112
	v_fma_f32 v120, -v108, v100, v116
	v_div_fmas_f32 v120, v120, v112, v100
	v_div_fixup_f32 v100, v120, v104, v96
	v_div_scale_f32 v117, vcc, v97, v105, v97
	v_mul_f32_e32 v101, v117, v113
	v_fma_f32 v120, -v109, v101, v117
	v_fmac_f32_e32 v101, v120, v113
	v_fma_f32 v120, -v109, v101, v117
	v_div_fmas_f32 v120, v120, v113, v101
	v_div_fixup_f32 v101, v120, v105, v97
	v_div_scale_f32 v118, vcc, v98, v106, v98
	v_mul_f32_e32 v102, v118, v114
	v_fma_f32 v120, -v110, v102, v118
	v_fmac_f32_e32 v102, v120, v114
	v_fma_f32 v120, -v110, v102, v118
	v_div_fmas_f32 v120, v120, v114, v102
	v_div_fixup_f32 v102, v120, v106, v98
	v_div_scale_f32 v119, vcc, v99, v107, v99
	v_mul_f32_e32 v103, v119, v115
	v_fma_f32 v120, -v111, v103, v119
	v_fmac_f32_e32 v103, v120, v115
	v_fma_f32 v120, -v111, v103, v119
	v_div_fmas_f32 v120, v120, v115, v103
	v_div_fixup_f32 v103, v120, v107, v99
	s_waitcnt lgkmcnt(0)
; __device__ __forceinline__ float bflo(unsigned w) { return __uint_as_float(w << 16); }
; __device__ __forceinline__ float bfhi(unsigned w) { return __uint_as_float(w & 0xffff0000u); }
; __device__ __forceinline__ float silu_f(float x) { return x / (1.0f + __expf(-x)); }
; __device__ void da_unit(char* lds, const Params& p, int layer, int unit) {
;     ...
; #pragma unroll
;         for (int k = 0; k < 4; ++k)
; #pragma unroll
;             for (int g = 0; g < 4; ++g) {
;                 const int d0 = 32 * k + 8 * g + 4 * h2;
;                 const f32x4 gg = *(const f32x4*)(sg + d0);
;                 const u32x2 gw = gwv[k * 4 + g];
;                 const float o0 = O[k][4 * g + 0] * rstd * gg[0] * silu_f(bflo(gw.x));
;                 const float o1 = O[k][4 * g + 1] * rstd * gg[1] * silu_f(bfhi(gw.x));
;                 const float o2 = O[k][4 * g + 2] * rstd * gg[2] * silu_f(bflo(gw.y));
;                 const float o3 = O[k][4 * g + 3] * rstd * gg[3] * silu_f(bfhi(gw.y));
;                 u32x2 w; w.x = cvt_pk_bf16(o0, o1); w.y = cvt_pk_bf16(o2, o3);
;                 *(u32x2*)(p.o + tokq * 1024 + h * 128 + d0) = w;
;             }
	v_mul_f32_e32 v56, v56, v70
	v_mul_f32_e32 v56, v56, v216
	v_mul_f32_e32 v56, v56, v100
	v_mul_f32_e32 v57, v57, v70
	v_mul_f32_e32 v57, v57, v217
	v_mul_f32_e32 v57, v57, v101
	v_mul_f32_e32 v58, v58, v70
	v_mul_f32_e32 v58, v58, v218
	v_mul_f32_e32 v58, v58, v102
	v_mul_f32_e32 v59, v59, v70
	v_mul_f32_e32 v59, v59, v219
	v_mul_f32_e32 v59, v59, v103
	v_cvt_pk_bf16_f32 v96, v56, v57
	v_cvt_pk_bf16_f32 v97, v58, v59
	global_store_dwordx2 v[78:79], v[96:97], off offset:32
	ds_read_b128 v[216:219], v72 offset:96
	v_lshlrev_b32_e32 v96, 16, v206
	v_and_b32_e32 v97, 0xffff0000, v206
	v_lshlrev_b32_e32 v98, 16, v207
	v_and_b32_e32 v99, 0xffff0000, v207
	v_mul_f32_e32 v104, 0xbfb8aa3b, v96
	v_mul_f32_e32 v105, 0xbfb8aa3b, v97
	v_mul_f32_e32 v106, 0xbfb8aa3b, v98
	v_mul_f32_e32 v107, 0xbfb8aa3b, v99
	v_exp_f32_e32 v104, v104
	v_exp_f32_e32 v105, v105
	v_exp_f32_e32 v106, v106
	v_exp_f32_e32 v107, v107
	v_add_f32_e32 v104, 1.0, v104
	v_add_f32_e32 v105, 1.0, v105
	v_add_f32_e32 v106, 1.0, v106
	v_add_f32_e32 v107, 1.0, v107
	v_div_scale_f32 v108, s[0:1], v104, v104, v96
	v_div_scale_f32 v109, s[0:1], v105, v105, v97
	v_div_scale_f32 v110, s[0:1], v106, v106, v98
	v_div_scale_f32 v111, s[0:1], v107, v107, v99
	v_rcp_f32_e32 v112, v108
	v_rcp_f32_e32 v113, v109
	v_rcp_f32_e32 v114, v110
	v_rcp_f32_e32 v115, v111
	v_fma_f32 v100, -v108, v112, 1.0
	v_fma_f32 v101, -v109, v113, 1.0
	v_fma_f32 v102, -v110, v114, 1.0
	v_fma_f32 v103, -v111, v115, 1.0
	v_fmac_f32_e32 v112, v100, v112
	v_fmac_f32_e32 v113, v101, v113
	v_fmac_f32_e32 v114, v102, v114
	v_fmac_f32_e32 v115, v103, v115
	v_div_scale_f32 v116, vcc, v96, v104, v96
	v_mul_f32_e32 v100, v116, v112
	v_fma_f32 v120, -v108, v100, v116
	v_fmac_f32_e32 v100, v120, v112
	v_fma_f32 v120, -v108, v100, v116
	v_div_fmas_f32 v120, v120, v112, v100
	v_div_fixup_f32 v100, v120, v104, v96
	v_div_scale_f32 v117, vcc, v97, v105, v97
	v_mul_f32_e32 v101, v117, v113
	v_fma_f32 v120, -v109, v101, v117
	v_fmac_f32_e32 v101, v120, v113
	v_fma_f32 v120, -v109, v101, v117
	v_div_fmas_f32 v120, v120, v113, v101
	v_div_fixup_f32 v101, v120, v105, v97
	v_div_scale_f32 v118, vcc, v98, v106, v98
	v_mul_f32_e32 v102, v118, v114
	v_fma_f32 v120, -v110, v102, v118
	v_fmac_f32_e32 v102, v120, v114
	v_fma_f32 v120, -v110, v102, v118
	v_div_fmas_f32 v120, v120, v114, v102
	v_div_fixup_f32 v102, v120, v106, v98
	v_div_scale_f32 v119, vcc, v99, v107, v99
	v_mul_f32_e32 v103, v119, v115
	v_fma_f32 v120, -v111, v103, v119
	v_fmac_f32_e32 v103, v120, v115
	v_fma_f32 v120, -v111, v103, v119
	v_div_fmas_f32 v120, v120, v115, v103
	v_div_fixup_f32 v103, v120, v107, v99
	s_waitcnt lgkmcnt(0)
	v_mul_f32_e32 v60, v60, v70
	v_mul_f32_e32 v60, v60, v216
	v_mul_f32_e32 v60, v60, v100
	v_mul_f32_e32 v61, v61, v70
	v_mul_f32_e32 v61, v61, v217
	v_mul_f32_e32 v61, v61, v101
	v_mul_f32_e32 v62, v62, v70
	v_mul_f32_e32 v62, v62, v218
	v_mul_f32_e32 v62, v62, v102
	v_mul_f32_e32 v63, v63, v70
	v_mul_f32_e32 v63, v63, v219
	v_mul_f32_e32 v63, v63, v103
	v_cvt_pk_bf16_f32 v96, v60, v61
	v_cvt_pk_bf16_f32 v97, v62, v63
	global_store_dwordx2 v[78:79], v[96:97], off offset:48
	ds_read_b128 v[216:219], v72 offset:128
	v_lshlrev_b32_e32 v96, 16, v208
	v_and_b32_e32 v97, 0xffff0000, v208
	v_lshlrev_b32_e32 v98, 16, v209
	v_and_b32_e32 v99, 0xffff0000, v209
	v_mul_f32_e32 v104, 0xbfb8aa3b, v96
	v_mul_f32_e32 v105, 0xbfb8aa3b, v97
	v_mul_f32_e32 v106, 0xbfb8aa3b, v98
	v_mul_f32_e32 v107, 0xbfb8aa3b, v99
	v_exp_f32_e32 v104, v104
	v_exp_f32_e32 v105, v105
	v_exp_f32_e32 v106, v106
	v_exp_f32_e32 v107, v107
	v_add_f32_e32 v104, 1.0, v104
	v_add_f32_e32 v105, 1.0, v105
	v_add_f32_e32 v106, 1.0, v106
	v_add_f32_e32 v107, 1.0, v107
	v_div_scale_f32 v108, s[0:1], v104, v104, v96
	v_div_scale_f32 v109, s[0:1], v105, v105, v97
	v_div_scale_f32 v110, s[0:1], v106, v106, v98
	v_div_scale_f32 v111, s[0:1], v107, v107, v99
	v_rcp_f32_e32 v112, v108
	v_rcp_f32_e32 v113, v109
	v_rcp_f32_e32 v114, v110
	v_rcp_f32_e32 v115, v111
	v_fma_f32 v100, -v108, v112, 1.0
	v_fma_f32 v101, -v109, v113, 1.0
	v_fma_f32 v102, -v110, v114, 1.0
	v_fma_f32 v103, -v111, v115, 1.0
	v_fmac_f32_e32 v112, v100, v112
	v_fmac_f32_e32 v113, v101, v113
	v_fmac_f32_e32 v114, v102, v114
	v_fmac_f32_e32 v115, v103, v115
	v_div_scale_f32 v116, vcc, v96, v104, v96
	v_mul_f32_e32 v100, v116, v112
	v_fma_f32 v120, -v108, v100, v116
	v_fmac_f32_e32 v100, v120, v112
	v_fma_f32 v120, -v108, v100, v116
	v_div_fmas_f32 v120, v120, v112, v100
	v_div_fixup_f32 v100, v120, v104, v96
	v_div_scale_f32 v117, vcc, v97, v105, v97
	v_mul_f32_e32 v101, v117, v113
	v_fma_f32 v120, -v109, v101, v117
	v_fmac_f32_e32 v101, v120, v113
	v_fma_f32 v120, -v109, v101, v117
	v_div_fmas_f32 v120, v120, v113, v101
	v_div_fixup_f32 v101, v120, v105, v97
	v_div_scale_f32 v118, vcc, v98, v106, v98
	v_mul_f32_e32 v102, v118, v114
	v_fma_f32 v120, -v110, v102, v118
	v_fmac_f32_e32 v102, v120, v114
	v_fma_f32 v120, -v110, v102, v118
	v_div_fmas_f32 v120, v120, v114, v102
	v_div_fixup_f32 v102, v120, v106, v98
	v_div_scale_f32 v119, vcc, v99, v107, v99
	v_mul_f32_e32 v103, v119, v115
	v_fma_f32 v120, -v111, v103, v119
	v_fmac_f32_e32 v103, v120, v115
	v_fma_f32 v120, -v111, v103, v119
	v_div_fmas_f32 v120, v120, v115, v103
	v_div_fixup_f32 v103, v120, v107, v99
	s_waitcnt lgkmcnt(0)
; __device__ __forceinline__ float bflo(unsigned w) { return __uint_as_float(w << 16); }
; __device__ __forceinline__ float bfhi(unsigned w) { return __uint_as_float(w & 0xffff0000u); }
; __device__ __forceinline__ float silu_f(float x) { return x / (1.0f + __expf(-x)); }
; __device__ void da_unit(char* lds, const Params& p, int layer, int unit) {
;     ...
; #pragma unroll
;         for (int k = 0; k < 4; ++k)
; #pragma unroll
;             for (int g = 0; g < 4; ++g) {
;                 const int d0 = 32 * k + 8 * g + 4 * h2;
;                 const f32x4 gg = *(const f32x4*)(sg + d0);
;                 const u32x2 gw = gwv[k * 4 + g];
;                 const float o0 = O[k][4 * g + 0] * rstd * gg[0] * silu_f(bflo(gw.x));
;                 const float o1 = O[k][4 * g + 1] * rstd * gg[1] * silu_f(bfhi(gw.x));
;                 const float o2 = O[k][4 * g + 2] * rstd * gg[2] * silu_f(bflo(gw.y));
;                 const float o3 = O[k][4 * g + 3] * rstd * gg[3] * silu_f(bfhi(gw.y));
;                 u32x2 w; w.x = cvt_pk_bf16(o0, o1); w.y = cvt_pk_bf16(o2, o3);
;                 *(u32x2*)(p.o + tokq * 1024 + h * 128 + d0) = w;
;             }
	v_mul_f32_e32 v32, v32, v70
	v_mul_f32_e32 v32, v32, v216
	v_mul_f32_e32 v32, v32, v100
	v_mul_f32_e32 v33, v33, v70
	v_mul_f32_e32 v33, v33, v217
	v_mul_f32_e32 v33, v33, v101
	v_mul_f32_e32 v34, v34, v70
	v_mul_f32_e32 v34, v34, v218
	v_mul_f32_e32 v34, v34, v102
	v_mul_f32_e32 v35, v35, v70
	v_mul_f32_e32 v35, v35, v219
	v_mul_f32_e32 v35, v35, v103
	v_cvt_pk_bf16_f32 v96, v32, v33
	v_cvt_pk_bf16_f32 v97, v34, v35
	global_store_dwordx2 v[78:79], v[96:97], off offset:64
	ds_read_b128 v[216:219], v72 offset:160
	v_lshlrev_b32_e32 v96, 16, v210
	v_and_b32_e32 v97, 0xffff0000, v210
	v_lshlrev_b32_e32 v98, 16, v211
	v_and_b32_e32 v99, 0xffff0000, v211
	v_mul_f32_e32 v104, 0xbfb8aa3b, v96
	v_mul_f32_e32 v105, 0xbfb8aa3b, v97
	v_mul_f32_e32 v106, 0xbfb8aa3b, v98
	v_mul_f32_e32 v107, 0xbfb8aa3b, v99
	v_exp_f32_e32 v104, v104
	v_exp_f32_e32 v105, v105
	v_exp_f32_e32 v106, v106
	v_exp_f32_e32 v107, v107
	v_add_f32_e32 v104, 1.0, v104
	v_add_f32_e32 v105, 1.0, v105
	v_add_f32_e32 v106, 1.0, v106
	v_add_f32_e32 v107, 1.0, v107
	v_div_scale_f32 v108, s[0:1], v104, v104, v96
	v_div_scale_f32 v109, s[0:1], v105, v105, v97
	v_div_scale_f32 v110, s[0:1], v106, v106, v98
	v_div_scale_f32 v111, s[0:1], v107, v107, v99
	v_rcp_f32_e32 v112, v108
	v_rcp_f32_e32 v113, v109
	v_rcp_f32_e32 v114, v110
	v_rcp_f32_e32 v115, v111
	v_fma_f32 v100, -v108, v112, 1.0
	v_fma_f32 v101, -v109, v113, 1.0
	v_fma_f32 v102, -v110, v114, 1.0
	v_fma_f32 v103, -v111, v115, 1.0
	v_fmac_f32_e32 v112, v100, v112
	v_fmac_f32_e32 v113, v101, v113
	v_fmac_f32_e32 v114, v102, v114
	v_fmac_f32_e32 v115, v103, v115
	v_div_scale_f32 v116, vcc, v96, v104, v96
	v_mul_f32_e32 v100, v116, v112
	v_fma_f32 v120, -v108, v100, v116
	v_fmac_f32_e32 v100, v120, v112
	v_fma_f32 v120, -v108, v100, v116
	v_div_fmas_f32 v120, v120, v112, v100
	v_div_fixup_f32 v100, v120, v104, v96
	v_div_scale_f32 v117, vcc, v97, v105, v97
	v_mul_f32_e32 v101, v117, v113
	v_fma_f32 v120, -v109, v101, v117
	v_fmac_f32_e32 v101, v120, v113
	v_fma_f32 v120, -v109, v101, v117
	v_div_fmas_f32 v120, v120, v113, v101
	v_div_fixup_f32 v101, v120, v105, v97
	v_div_scale_f32 v118, vcc, v98, v106, v98
	v_mul_f32_e32 v102, v118, v114
	v_fma_f32 v120, -v110, v102, v118
	v_fmac_f32_e32 v102, v120, v114
	v_fma_f32 v120, -v110, v102, v118
	v_div_fmas_f32 v120, v120, v114, v102
	v_div_fixup_f32 v102, v120, v106, v98
	v_div_scale_f32 v119, vcc, v99, v107, v99
	v_mul_f32_e32 v103, v119, v115
	v_fma_f32 v120, -v111, v103, v119
	v_fmac_f32_e32 v103, v120, v115
	v_fma_f32 v120, -v111, v103, v119
	v_div_fmas_f32 v120, v120, v115, v103
	v_div_fixup_f32 v103, v120, v107, v99
	s_waitcnt lgkmcnt(0)
	v_mul_f32_e32 v36, v36, v70
	v_mul_f32_e32 v36, v36, v216
	v_mul_f32_e32 v36, v36, v100
	v_mul_f32_e32 v37, v37, v70
	v_mul_f32_e32 v37, v37, v217
	v_mul_f32_e32 v37, v37, v101
	v_mul_f32_e32 v38, v38, v70
	v_mul_f32_e32 v38, v38, v218
	v_mul_f32_e32 v38, v38, v102
	v_mul_f32_e32 v39, v39, v70
	v_mul_f32_e32 v39, v39, v219
	v_mul_f32_e32 v39, v39, v103
	v_cvt_pk_bf16_f32 v96, v36, v37
	v_cvt_pk_bf16_f32 v97, v38, v39
	global_store_dwordx2 v[78:79], v[96:97], off offset:80
	ds_read_b128 v[216:219], v72 offset:192
	v_lshlrev_b32_e32 v96, 16, v212
	v_and_b32_e32 v97, 0xffff0000, v212
	v_lshlrev_b32_e32 v98, 16, v213
	v_and_b32_e32 v99, 0xffff0000, v213
	v_mul_f32_e32 v104, 0xbfb8aa3b, v96
	v_mul_f32_e32 v105, 0xbfb8aa3b, v97
	v_mul_f32_e32 v106, 0xbfb8aa3b, v98
	v_mul_f32_e32 v107, 0xbfb8aa3b, v99
	v_exp_f32_e32 v104, v104
	v_exp_f32_e32 v105, v105
	v_exp_f32_e32 v106, v106
	v_exp_f32_e32 v107, v107
	v_add_f32_e32 v104, 1.0, v104
	v_add_f32_e32 v105, 1.0, v105
	v_add_f32_e32 v106, 1.0, v106
	v_add_f32_e32 v107, 1.0, v107
	v_div_scale_f32 v108, s[0:1], v104, v104, v96
	v_div_scale_f32 v109, s[0:1], v105, v105, v97
	v_div_scale_f32 v110, s[0:1], v106, v106, v98
	v_div_scale_f32 v111, s[0:1], v107, v107, v99
	v_rcp_f32_e32 v112, v108
	v_rcp_f32_e32 v113, v109
	v_rcp_f32_e32 v114, v110
	v_rcp_f32_e32 v115, v111
	v_fma_f32 v100, -v108, v112, 1.0
	v_fma_f32 v101, -v109, v113, 1.0
	v_fma_f32 v102, -v110, v114, 1.0
	v_fma_f32 v103, -v111, v115, 1.0
	v_fmac_f32_e32 v112, v100, v112
	v_fmac_f32_e32 v113, v101, v113
	v_fmac_f32_e32 v114, v102, v114
	v_fmac_f32_e32 v115, v103, v115
	v_div_scale_f32 v116, vcc, v96, v104, v96
	v_mul_f32_e32 v100, v116, v112
	v_fma_f32 v120, -v108, v100, v116
	v_fmac_f32_e32 v100, v120, v112
	v_fma_f32 v120, -v108, v100, v116
	v_div_fmas_f32 v120, v120, v112, v100
	v_div_fixup_f32 v100, v120, v104, v96
	v_div_scale_f32 v117, vcc, v97, v105, v97
	v_mul_f32_e32 v101, v117, v113
	v_fma_f32 v120, -v109, v101, v117
	v_fmac_f32_e32 v101, v120, v113
	v_fma_f32 v120, -v109, v101, v117
	v_div_fmas_f32 v120, v120, v113, v101
	v_div_fixup_f32 v101, v120, v105, v97
	v_div_scale_f32 v118, vcc, v98, v106, v98
	v_mul_f32_e32 v102, v118, v114
	v_fma_f32 v120, -v110, v102, v118
	v_fmac_f32_e32 v102, v120, v114
	v_fma_f32 v120, -v110, v102, v118
	v_div_fmas_f32 v120, v120, v114, v102
	v_div_fixup_f32 v102, v120, v106, v98
	v_div_scale_f32 v119, vcc, v99, v107, v99
	v_mul_f32_e32 v103, v119, v115
	v_fma_f32 v120, -v111, v103, v119
	v_fmac_f32_e32 v103, v120, v115
	v_fma_f32 v120, -v111, v103, v119
	v_div_fmas_f32 v120, v120, v115, v103
	v_div_fixup_f32 v103, v120, v107, v99
	s_waitcnt lgkmcnt(0)
; __device__ __forceinline__ float bflo(unsigned w) { return __uint_as_float(w << 16); }
; __device__ __forceinline__ float bfhi(unsigned w) { return __uint_as_float(w & 0xffff0000u); }
; __device__ __forceinline__ float silu_f(float x) { return x / (1.0f + __expf(-x)); }
; __device__ void da_unit(char* lds, const Params& p, int layer, int unit) {
;     ...
;     if (c == 1) {
;         const float i1 = lam / lsum;
; #pragma unroll
;         for (int k = 0; k < 4; ++k)
; #pragma unroll
;             for (int e = 0; e < 16; ++e) xch[(k * 16 + e) * 64 + lane] = O[k][e] * i1;
;     }
;     __syncthreads();
;     if (c == 0) {
;         const float i0 = 1.0f / lsum;
;         float ss = 0.f;
; #pragma unroll
;         for (int k = 0; k < 4; ++k)
; #pragma unroll
;             for (int e = 0; e < 16; ++e) { const float a = O[k][e] * i0 - xch[(k * 16 + e) * 64 + lane]; O[k][e] = a; ss += a * a; }
;         ss += __shfl_xor(ss, 32);
;     ...
;             for (int g = 0; g < 4; ++g) {
;                 const int d0 = 32 * k + 8 * g + 4 * h2;
;                 const f32x4 gg = *(const f32x4*)(sg + d0);
;                 const u32x2 gw = gwv[k * 4 + g];
;                 const float o0 = O[k][4 * g + 0] * rstd * gg[0] * silu_f(bflo(gw.x));
;                 const float o1 = O[k][4 * g + 1] * rstd * gg[1] * silu_f(bfhi(gw.x));
;                 const float o2 = O[k][4 * g + 2] * rstd * gg[2] * silu_f(bflo(gw.y));
;                 const float o3 = O[k][4 * g + 3] * rstd * gg[3] * silu_f(bfhi(gw.y));
;                 u32x2 w; w.x = cvt_pk_bf16(o0, o1); w.y = cvt_pk_bf16(o2, o3);
;                 *(u32x2*)(p.o + tokq * 1024 + h * 128 + d0) = w;
	v_mul_f32_e32 v40, v40, v70
	v_mul_f32_e32 v40, v40, v216
	v_mul_f32_e32 v40, v40, v100
	v_mul_f32_e32 v41, v41, v70
	v_mul_f32_e32 v41, v41, v217
	v_mul_f32_e32 v41, v41, v101
	v_mul_f32_e32 v42, v42, v70
	v_mul_f32_e32 v42, v42, v218
	v_mul_f32_e32 v42, v42, v102
	v_mul_f32_e32 v43, v43, v70
	v_mul_f32_e32 v43, v43, v219
	v_mul_f32_e32 v43, v43, v103
	v_cvt_pk_bf16_f32 v96, v40, v41
	v_cvt_pk_bf16_f32 v97, v42, v43
	global_store_dwordx2 v[78:79], v[96:97], off offset:96
	ds_read_b128 v[216:219], v72 offset:224
	v_lshlrev_b32_e32 v96, 16, v214
	v_and_b32_e32 v97, 0xffff0000, v214
	v_lshlrev_b32_e32 v98, 16, v215
	v_and_b32_e32 v99, 0xffff0000, v215
	v_mul_f32_e32 v104, 0xbfb8aa3b, v96
	v_mul_f32_e32 v105, 0xbfb8aa3b, v97
	v_mul_f32_e32 v106, 0xbfb8aa3b, v98
	v_mul_f32_e32 v107, 0xbfb8aa3b, v99
	v_exp_f32_e32 v104, v104
	v_exp_f32_e32 v105, v105
	v_exp_f32_e32 v106, v106
	v_exp_f32_e32 v107, v107
	v_add_f32_e32 v104, 1.0, v104
	v_add_f32_e32 v105, 1.0, v105
	v_add_f32_e32 v106, 1.0, v106
	v_add_f32_e32 v107, 1.0, v107
	v_div_scale_f32 v108, s[0:1], v104, v104, v96
	v_div_scale_f32 v109, s[0:1], v105, v105, v97
	v_div_scale_f32 v110, s[0:1], v106, v106, v98
	v_div_scale_f32 v111, s[0:1], v107, v107, v99
	v_rcp_f32_e32 v112, v108
	v_rcp_f32_e32 v113, v109
	v_rcp_f32_e32 v114, v110
	v_rcp_f32_e32 v115, v111
	v_fma_f32 v100, -v108, v112, 1.0
	v_fma_f32 v101, -v109, v113, 1.0
	v_fma_f32 v102, -v110, v114, 1.0
	v_fma_f32 v103, -v111, v115, 1.0
	v_fmac_f32_e32 v112, v100, v112
	v_fmac_f32_e32 v113, v101, v113
	v_fmac_f32_e32 v114, v102, v114
	v_fmac_f32_e32 v115, v103, v115
	v_div_scale_f32 v116, vcc, v96, v104, v96
	v_mul_f32_e32 v100, v116, v112
	v_fma_f32 v120, -v108, v100, v116
	v_fmac_f32_e32 v100, v120, v112
	v_fma_f32 v120, -v108, v100, v116
	v_div_fmas_f32 v120, v120, v112, v100
	v_div_fixup_f32 v100, v120, v104, v96
	v_div_scale_f32 v117, vcc, v97, v105, v97
	v_mul_f32_e32 v101, v117, v113
	v_fma_f32 v120, -v109, v101, v117
	v_fmac_f32_e32 v101, v120, v113
	v_fma_f32 v120, -v109, v101, v117
	v_div_fmas_f32 v120, v120, v113, v101
	v_div_fixup_f32 v101, v120, v105, v97
	v_div_scale_f32 v118, vcc, v98, v106, v98
	v_mul_f32_e32 v102, v118, v114
	v_fma_f32 v120, -v110, v102, v118
	v_fmac_f32_e32 v102, v120, v114
	v_fma_f32 v120, -v110, v102, v118
	v_div_fmas_f32 v120, v120, v114, v102
	v_div_fixup_f32 v102, v120, v106, v98
	v_div_scale_f32 v119, vcc, v99, v107, v99
	v_mul_f32_e32 v103, v119, v115
	v_fma_f32 v120, -v111, v103, v119
	v_fmac_f32_e32 v103, v120, v115
	v_fma_f32 v120, -v111, v103, v119
	v_div_fmas_f32 v120, v120, v115, v103
	v_div_fixup_f32 v103, v120, v107, v99
	s_waitcnt lgkmcnt(0)
	v_mul_f32_e32 v44, v44, v70
	v_mul_f32_e32 v44, v44, v216
	v_mul_f32_e32 v44, v44, v100
	v_mul_f32_e32 v45, v45, v70
	v_mul_f32_e32 v45, v45, v217
	v_mul_f32_e32 v45, v45, v101
	v_mul_f32_e32 v46, v46, v70
	v_mul_f32_e32 v46, v46, v218
	v_mul_f32_e32 v46, v46, v102
	v_mul_f32_e32 v47, v47, v70
	v_mul_f32_e32 v47, v47, v219
	v_mul_f32_e32 v47, v47, v103
	v_cvt_pk_bf16_f32 v96, v44, v45
	v_cvt_pk_bf16_f32 v97, v46, v47
	global_store_dwordx2 v[78:79], v[96:97], off offset:112
	s_branch .LBB0_450
.Ldt_c1:
	ds_write2st64_b32 v67, v48, v49 offset0:0 offset1:1
	ds_write2st64_b32 v67, v50, v51 offset0:2 offset1:3
	ds_write2st64_b32 v67, v52, v53 offset0:4 offset1:5
	ds_write2st64_b32 v67, v54, v55 offset0:6 offset1:7
	ds_write2st64_b32 v67, v56, v57 offset0:8 offset1:9
	ds_write2st64_b32 v67, v58, v59 offset0:10 offset1:11
	ds_write2st64_b32 v67, v60, v61 offset0:12 offset1:13
	ds_write2st64_b32 v67, v62, v63 offset0:14 offset1:15
	ds_write2st64_b32 v67, v32, v33 offset0:16 offset1:17
	ds_write2st64_b32 v67, v34, v35 offset0:18 offset1:19
	ds_write2st64_b32 v67, v36, v37 offset0:20 offset1:21
	ds_write2st64_b32 v67, v38, v39 offset0:22 offset1:23
	ds_write2st64_b32 v67, v40, v41 offset0:24 offset1:25
	ds_write2st64_b32 v67, v42, v43 offset0:26 offset1:27
	ds_write2st64_b32 v67, v44, v45 offset0:28 offset1:29
	ds_write2st64_b32 v67, v46, v47 offset0:30 offset1:31
	s_waitcnt lgkmcnt(0)
	s_barrier
	ds_read2st64_b32 v[80:81], v67 offset0:32 offset1:33
	ds_read2st64_b32 v[82:83], v67 offset0:34 offset1:35
	ds_read2st64_b32 v[84:85], v67 offset0:36 offset1:37
	ds_read2st64_b32 v[86:87], v67 offset0:38 offset1:39
	ds_read2st64_b32 v[88:89], v67 offset0:40 offset1:41
	ds_read2st64_b32 v[90:91], v67 offset0:42 offset1:43
	ds_read2st64_b32 v[92:93], v67 offset0:44 offset1:45
	ds_read2st64_b32 v[94:95], v67 offset0:46 offset1:47
	s_waitcnt lgkmcnt(0)
	v_add_f32_e32 v16, v16, v80
	v_add_f32_e32 v17, v17, v81
	v_add_f32_e32 v18, v18, v82
	v_add_f32_e32 v19, v19, v83
	v_add_f32_e32 v20, v20, v84
	v_add_f32_e32 v21, v21, v85
	v_add_f32_e32 v22, v22, v86
	v_add_f32_e32 v23, v23, v87
	v_add_f32_e32 v24, v24, v88
	v_add_f32_e32 v25, v25, v89
	v_add_f32_e32 v26, v26, v90
	v_add_f32_e32 v27, v27, v91
	v_add_f32_e32 v28, v28, v92
	v_add_f32_e32 v29, v29, v93
	v_add_f32_e32 v30, v30, v94
	v_add_f32_e32 v31, v31, v95
	v_mul_f32_e32 v69, v16, v16
	v_fmac_f32_e32 v69, v17, v17
	v_fmac_f32_e32 v69, v18, v18
	v_fmac_f32_e32 v69, v19, v19
	v_fmac_f32_e32 v69, v20, v20
	v_fmac_f32_e32 v69, v21, v21
	v_fmac_f32_e32 v69, v22, v22
	v_fmac_f32_e32 v69, v23, v23
	v_fmac_f32_e32 v69, v24, v24
	v_fmac_f32_e32 v69, v25, v25
	v_fmac_f32_e32 v69, v26, v26
	v_fmac_f32_e32 v69, v27, v27
	v_fmac_f32_e32 v69, v28, v28
	v_fmac_f32_e32 v69, v29, v29
	v_fmac_f32_e32 v69, v30, v30
	v_fmac_f32_e32 v69, v31, v31
	ds_read2st64_b32 v[80:81], v67 offset0:48 offset1:49
	ds_read2st64_b32 v[82:83], v67 offset0:50 offset1:51
	ds_read2st64_b32 v[84:85], v67 offset0:52 offset1:53
	ds_read2st64_b32 v[86:87], v67 offset0:54 offset1:55
	ds_read2st64_b32 v[88:89], v67 offset0:56 offset1:57
	ds_read2st64_b32 v[90:91], v67 offset0:58 offset1:59
	ds_read2st64_b32 v[92:93], v67 offset0:60 offset1:61
	ds_read2st64_b32 v[94:95], v67 offset0:62 offset1:63
	s_waitcnt lgkmcnt(0)
	v_add_f32_e32 v0, v0, v80
	v_add_f32_e32 v1, v1, v81
	v_add_f32_e32 v2, v2, v82
	v_add_f32_e32 v3, v3, v83
	v_add_f32_e32 v4, v4, v84
	v_add_f32_e32 v5, v5, v85
	v_add_f32_e32 v6, v6, v86
	v_add_f32_e32 v7, v7, v87
	v_add_f32_e32 v8, v8, v88
	v_add_f32_e32 v9, v9, v89
	v_add_f32_e32 v10, v10, v90
	v_add_f32_e32 v11, v11, v91
	v_add_f32_e32 v12, v12, v92
	v_add_f32_e32 v13, v13, v93
	v_add_f32_e32 v14, v14, v94
	v_add_f32_e32 v15, v15, v95
	v_fmac_f32_e32 v69, v0, v0
	v_fmac_f32_e32 v69, v1, v1
	v_fmac_f32_e32 v69, v2, v2
	v_fmac_f32_e32 v69, v3, v3
	v_fmac_f32_e32 v69, v4, v4
	v_fmac_f32_e32 v69, v5, v5
	v_fmac_f32_e32 v69, v6, v6
	v_fmac_f32_e32 v69, v7, v7
	v_fmac_f32_e32 v69, v8, v8
	v_fmac_f32_e32 v69, v9, v9
	v_fmac_f32_e32 v69, v10, v10
	v_fmac_f32_e32 v69, v11, v11
	v_fmac_f32_e32 v69, v12, v12
	v_fmac_f32_e32 v69, v13, v13
	v_fmac_f32_e32 v69, v14, v14
	v_fmac_f32_e32 v69, v15, v15
	ds_bpermute_b32 v72, v244, v69
	s_waitcnt lgkmcnt(0)
	v_add_f32_e32 v69, v69, v72
	ds_write_b32 v68, v69
	s_waitcnt lgkmcnt(0)
	s_barrier
; __device__ __forceinline__ float bflo(unsigned w) { return __uint_as_float(w << 16); }
; __device__ __forceinline__ float bfhi(unsigned w) { return __uint_as_float(w & 0xffff0000u); }
; __device__ __forceinline__ float silu_f(float x) { return x / (1.0f + __expf(-x)); }
; __device__ void da_unit(char* lds, const Params& p, int layer, int unit) {
;     ...
;         ss += __shfl_xor(ss, 32);
;         const float rstd = rsqrtf(ss * (1.0f / 128.0f) + RMS_EPS) * (1.0f - p.lam_init[layer]);
;         const float* sg = (const float*)(lds + LDS_SG_OFF);
;         __builtin_amdgcn_sched_barrier(0);
; #pragma unroll
;         for (int k = 0; k < 4; ++k)
; #pragma unroll
;             for (int g = 0; g < 4; ++g) {
;                 const int d0 = 32 * k + 8 * g + 4 * h2;
;                 const f32x4 gg = *(const f32x4*)(sg + d0);
;                 const u32x2 gw = gwv[k * 4 + g];
;                 const float o0 = O[k][4 * g + 0] * rstd * gg[0] * silu_f(bflo(gw.x));
;                 const float o1 = O[k][4 * g + 1] * rstd * gg[1] * silu_f(bfhi(gw.x));
;                 const float o2 = O[k][4 * g + 2] * rstd * gg[2] * silu_f(bflo(gw.y));
;                 const float o3 = O[k][4 * g + 3] * rstd * gg[3] * silu_f(bfhi(gw.y));
;                 u32x2 w; w.x = cvt_pk_bf16(o0, o1); w.y = cvt_pk_bf16(o2, o3);
;                 *(u32x2*)(p.o + tokq * 1024 + h * 128 + d0) = w;
	v_add_u32_e32 v73, 0xffffff00, v68
	ds_read_b32 v72, v73
	v_mov_b32_e32 v74, 0x358637bd
	v_sub_f32_e64 v75, 1.0, s2
	s_waitcnt lgkmcnt(0)
	v_add_f32_e32 v69, v69, v72
	v_fmamk_f32 v69, v69, 0x3c000000, v74
	v_rsq_f32_e32 v69, v69
	s_nop 0
	v_mul_f32_e32 v70, v75, v69
	v_lshl_add_u32 v72, v188, 4, 0
	v_add_u32_e32 v72, 0x26b30, v72
	s_waitcnt vmcnt(0)
	ds_read_b128 v[216:219], v72 offset:256
	v_lshlrev_b32_e32 v96, 16, v200
	v_and_b32_e32 v97, 0xffff0000, v200
	v_lshlrev_b32_e32 v98, 16, v201
	v_and_b32_e32 v99, 0xffff0000, v201
	v_mul_f32_e32 v104, 0xbfb8aa3b, v96
	v_mul_f32_e32 v105, 0xbfb8aa3b, v97
	v_mul_f32_e32 v106, 0xbfb8aa3b, v98
	v_mul_f32_e32 v107, 0xbfb8aa3b, v99
	v_exp_f32_e32 v104, v104
	v_exp_f32_e32 v105, v105
	v_exp_f32_e32 v106, v106
	v_exp_f32_e32 v107, v107
	v_add_f32_e32 v104, 1.0, v104
	v_add_f32_e32 v105, 1.0, v105
	v_add_f32_e32 v106, 1.0, v106
	v_add_f32_e32 v107, 1.0, v107
	v_div_scale_f32 v108, s[0:1], v104, v104, v96
	v_div_scale_f32 v109, s[0:1], v105, v105, v97
	v_div_scale_f32 v110, s[0:1], v106, v106, v98
	v_div_scale_f32 v111, s[0:1], v107, v107, v99
	v_rcp_f32_e32 v112, v108
	v_rcp_f32_e32 v113, v109
	v_rcp_f32_e32 v114, v110
	v_rcp_f32_e32 v115, v111
	v_fma_f32 v100, -v108, v112, 1.0
	v_fma_f32 v101, -v109, v113, 1.0
	v_fma_f32 v102, -v110, v114, 1.0
	v_fma_f32 v103, -v111, v115, 1.0
	v_fmac_f32_e32 v112, v100, v112
	v_fmac_f32_e32 v113, v101, v113
	v_fmac_f32_e32 v114, v102, v114
	v_fmac_f32_e32 v115, v103, v115
	v_div_scale_f32 v116, vcc, v96, v104, v96
	v_mul_f32_e32 v100, v116, v112
	v_fma_f32 v120, -v108, v100, v116
	v_fmac_f32_e32 v100, v120, v112
	v_fma_f32 v120, -v108, v100, v116
	v_div_fmas_f32 v120, v120, v112, v100
	v_div_fixup_f32 v100, v120, v104, v96
	v_div_scale_f32 v117, vcc, v97, v105, v97
	v_mul_f32_e32 v101, v117, v113
	v_fma_f32 v120, -v109, v101, v117
	v_fmac_f32_e32 v101, v120, v113
	v_fma_f32 v120, -v109, v101, v117
	v_div_fmas_f32 v120, v120, v113, v101
	v_div_fixup_f32 v101, v120, v105, v97
	v_div_scale_f32 v118, vcc, v98, v106, v98
	v_mul_f32_e32 v102, v118, v114
	v_fma_f32 v120, -v110, v102, v118
	v_fmac_f32_e32 v102, v120, v114
	v_fma_f32 v120, -v110, v102, v118
	v_div_fmas_f32 v120, v120, v114, v102
	v_div_fixup_f32 v102, v120, v106, v98
	v_div_scale_f32 v119, vcc, v99, v107, v99
	v_mul_f32_e32 v103, v119, v115
	v_fma_f32 v120, -v111, v103, v119
	v_fmac_f32_e32 v103, v120, v115
	v_fma_f32 v120, -v111, v103, v119
	v_div_fmas_f32 v120, v120, v115, v103
	v_div_fixup_f32 v103, v120, v107, v99
	s_waitcnt lgkmcnt(0)
	v_mul_f32_e32 v16, v16, v70
	v_mul_f32_e32 v16, v16, v216
	v_mul_f32_e32 v16, v16, v100
	v_mul_f32_e32 v17, v17, v70
	v_mul_f32_e32 v17, v17, v217
	v_mul_f32_e32 v17, v17, v101
	v_mul_f32_e32 v18, v18, v70
	v_mul_f32_e32 v18, v18, v218
	v_mul_f32_e32 v18, v18, v102
	v_mul_f32_e32 v19, v19, v70
	v_mul_f32_e32 v19, v19, v219
	v_mul_f32_e32 v19, v19, v103
	v_cvt_pk_bf16_f32 v96, v16, v17
	v_cvt_pk_bf16_f32 v97, v18, v19
	global_store_dwordx2 v[78:79], v[96:97], off offset:0
	ds_read_b128 v[216:219], v72 offset:288
	v_lshlrev_b32_e32 v96, 16, v202
	v_and_b32_e32 v97, 0xffff0000, v202
	v_lshlrev_b32_e32 v98, 16, v203
	v_and_b32_e32 v99, 0xffff0000, v203
	v_mul_f32_e32 v104, 0xbfb8aa3b, v96
	v_mul_f32_e32 v105, 0xbfb8aa3b, v97
	v_mul_f32_e32 v106, 0xbfb8aa3b, v98
	v_mul_f32_e32 v107, 0xbfb8aa3b, v99
	v_exp_f32_e32 v104, v104
	v_exp_f32_e32 v105, v105
	v_exp_f32_e32 v106, v106
	v_exp_f32_e32 v107, v107
	v_add_f32_e32 v104, 1.0, v104
	v_add_f32_e32 v105, 1.0, v105
	v_add_f32_e32 v106, 1.0, v106
	v_add_f32_e32 v107, 1.0, v107
	v_div_scale_f32 v108, s[0:1], v104, v104, v96
	v_div_scale_f32 v109, s[0:1], v105, v105, v97
	v_div_scale_f32 v110, s[0:1], v106, v106, v98
	v_div_scale_f32 v111, s[0:1], v107, v107, v99
	v_rcp_f32_e32 v112, v108
	v_rcp_f32_e32 v113, v109
	v_rcp_f32_e32 v114, v110
	v_rcp_f32_e32 v115, v111
	v_fma_f32 v100, -v108, v112, 1.0
	v_fma_f32 v101, -v109, v113, 1.0
	v_fma_f32 v102, -v110, v114, 1.0
	v_fma_f32 v103, -v111, v115, 1.0
	v_fmac_f32_e32 v112, v100, v112
	v_fmac_f32_e32 v113, v101, v113
	v_fmac_f32_e32 v114, v102, v114
	v_fmac_f32_e32 v115, v103, v115
	v_div_scale_f32 v116, vcc, v96, v104, v96
	v_mul_f32_e32 v100, v116, v112
	v_fma_f32 v120, -v108, v100, v116
	v_fmac_f32_e32 v100, v120, v112
	v_fma_f32 v120, -v108, v100, v116
	v_div_fmas_f32 v120, v120, v112, v100
	v_div_fixup_f32 v100, v120, v104, v96
	v_div_scale_f32 v117, vcc, v97, v105, v97
	v_mul_f32_e32 v101, v117, v113
	v_fma_f32 v120, -v109, v101, v117
	v_fmac_f32_e32 v101, v120, v113
	v_fma_f32 v120, -v109, v101, v117
	v_div_fmas_f32 v120, v120, v113, v101
	v_div_fixup_f32 v101, v120, v105, v97
	v_div_scale_f32 v118, vcc, v98, v106, v98
	v_mul_f32_e32 v102, v118, v114
	v_fma_f32 v120, -v110, v102, v118
	v_fmac_f32_e32 v102, v120, v114
	v_fma_f32 v120, -v110, v102, v118
	v_div_fmas_f32 v120, v120, v114, v102
	v_div_fixup_f32 v102, v120, v106, v98
	v_div_scale_f32 v119, vcc, v99, v107, v99
	v_mul_f32_e32 v103, v119, v115
	v_fma_f32 v120, -v111, v103, v119
	v_fmac_f32_e32 v103, v120, v115
	v_fma_f32 v120, -v111, v103, v119
	v_div_fmas_f32 v120, v120, v115, v103
	v_div_fixup_f32 v103, v120, v107, v99
	s_waitcnt lgkmcnt(0)
; __device__ __forceinline__ float bflo(unsigned w) { return __uint_as_float(w << 16); }
; __device__ __forceinline__ float bfhi(unsigned w) { return __uint_as_float(w & 0xffff0000u); }
; __device__ __forceinline__ float silu_f(float x) { return x / (1.0f + __expf(-x)); }
; __device__ void da_unit(char* lds, const Params& p, int layer, int unit) {
;     ...
;         for (int k = 0; k < 4; ++k)
; #pragma unroll
;             for (int g = 0; g < 4; ++g) {
;                 const int d0 = 32 * k + 8 * g + 4 * h2;
;                 const f32x4 gg = *(const f32x4*)(sg + d0);
;                 const u32x2 gw = gwv[k * 4 + g];
;                 const float o0 = O[k][4 * g + 0] * rstd * gg[0] * silu_f(bflo(gw.x));
;                 const float o1 = O[k][4 * g + 1] * rstd * gg[1] * silu_f(bfhi(gw.x));
;                 const float o2 = O[k][4 * g + 2] * rstd * gg[2] * silu_f(bflo(gw.y));
;                 const float o3 = O[k][4 * g + 3] * rstd * gg[3] * silu_f(bfhi(gw.y));
;                 u32x2 w; w.x = cvt_pk_bf16(o0, o1); w.y = cvt_pk_bf16(o2, o3);
;                 *(u32x2*)(p.o + tokq * 1024 + h * 128 + d0) = w;
	v_mul_f32_e32 v20, v20, v70
	v_mul_f32_e32 v20, v20, v216
	v_mul_f32_e32 v20, v20, v100
	v_mul_f32_e32 v21, v21, v70
	v_mul_f32_e32 v21, v21, v217
	v_mul_f32_e32 v21, v21, v101
	v_mul_f32_e32 v22, v22, v70
	v_mul_f32_e32 v22, v22, v218
	v_mul_f32_e32 v22, v22, v102
	v_mul_f32_e32 v23, v23, v70
	v_mul_f32_e32 v23, v23, v219
	v_mul_f32_e32 v23, v23, v103
	v_cvt_pk_bf16_f32 v96, v20, v21
	v_cvt_pk_bf16_f32 v97, v22, v23
	global_store_dwordx2 v[78:79], v[96:97], off offset:16
	ds_read_b128 v[216:219], v72 offset:320
	v_lshlrev_b32_e32 v96, 16, v204
	v_and_b32_e32 v97, 0xffff0000, v204
	v_lshlrev_b32_e32 v98, 16, v205
	v_and_b32_e32 v99, 0xffff0000, v205
	v_mul_f32_e32 v104, 0xbfb8aa3b, v96
	v_mul_f32_e32 v105, 0xbfb8aa3b, v97
	v_mul_f32_e32 v106, 0xbfb8aa3b, v98
	v_mul_f32_e32 v107, 0xbfb8aa3b, v99
	v_exp_f32_e32 v104, v104
	v_exp_f32_e32 v105, v105
	v_exp_f32_e32 v106, v106
	v_exp_f32_e32 v107, v107
	v_add_f32_e32 v104, 1.0, v104
	v_add_f32_e32 v105, 1.0, v105
	v_add_f32_e32 v106, 1.0, v106
	v_add_f32_e32 v107, 1.0, v107
	v_div_scale_f32 v108, s[0:1], v104, v104, v96
	v_div_scale_f32 v109, s[0:1], v105, v105, v97
	v_div_scale_f32 v110, s[0:1], v106, v106, v98
	v_div_scale_f32 v111, s[0:1], v107, v107, v99
	v_rcp_f32_e32 v112, v108
	v_rcp_f32_e32 v113, v109
	v_rcp_f32_e32 v114, v110
	v_rcp_f32_e32 v115, v111
	v_fma_f32 v100, -v108, v112, 1.0
	v_fma_f32 v101, -v109, v113, 1.0
	v_fma_f32 v102, -v110, v114, 1.0
	v_fma_f32 v103, -v111, v115, 1.0
	v_fmac_f32_e32 v112, v100, v112
	v_fmac_f32_e32 v113, v101, v113
	v_fmac_f32_e32 v114, v102, v114
	v_fmac_f32_e32 v115, v103, v115
	v_div_scale_f32 v116, vcc, v96, v104, v96
	v_mul_f32_e32 v100, v116, v112
	v_fma_f32 v120, -v108, v100, v116
	v_fmac_f32_e32 v100, v120, v112
	v_fma_f32 v120, -v108, v100, v116
	v_div_fmas_f32 v120, v120, v112, v100
	v_div_fixup_f32 v100, v120, v104, v96
	v_div_scale_f32 v117, vcc, v97, v105, v97
	v_mul_f32_e32 v101, v117, v113
	v_fma_f32 v120, -v109, v101, v117
	v_fmac_f32_e32 v101, v120, v113
	v_fma_f32 v120, -v109, v101, v117
	v_div_fmas_f32 v120, v120, v113, v101
	v_div_fixup_f32 v101, v120, v105, v97
	v_div_scale_f32 v118, vcc, v98, v106, v98
	v_mul_f32_e32 v102, v118, v114
	v_fma_f32 v120, -v110, v102, v118
	v_fmac_f32_e32 v102, v120, v114
	v_fma_f32 v120, -v110, v102, v118
	v_div_fmas_f32 v120, v120, v114, v102
	v_div_fixup_f32 v102, v120, v106, v98
	v_div_scale_f32 v119, vcc, v99, v107, v99
	v_mul_f32_e32 v103, v119, v115
	v_fma_f32 v120, -v111, v103, v119
	v_fmac_f32_e32 v103, v120, v115
	v_fma_f32 v120, -v111, v103, v119
	v_div_fmas_f32 v120, v120, v115, v103
	v_div_fixup_f32 v103, v120, v107, v99
	s_waitcnt lgkmcnt(0)
	v_mul_f32_e32 v24, v24, v70
	v_mul_f32_e32 v24, v24, v216
	v_mul_f32_e32 v24, v24, v100
	v_mul_f32_e32 v25, v25, v70
	v_mul_f32_e32 v25, v25, v217
	v_mul_f32_e32 v25, v25, v101
	v_mul_f32_e32 v26, v26, v70
	v_mul_f32_e32 v26, v26, v218
	v_mul_f32_e32 v26, v26, v102
	v_mul_f32_e32 v27, v27, v70
	v_mul_f32_e32 v27, v27, v219
	v_mul_f32_e32 v27, v27, v103
	v_cvt_pk_bf16_f32 v96, v24, v25
	v_cvt_pk_bf16_f32 v97, v26, v27
	global_store_dwordx2 v[78:79], v[96:97], off offset:32
	ds_read_b128 v[216:219], v72 offset:352
	v_lshlrev_b32_e32 v96, 16, v206
	v_and_b32_e32 v97, 0xffff0000, v206
	v_lshlrev_b32_e32 v98, 16, v207
	v_and_b32_e32 v99, 0xffff0000, v207
	v_mul_f32_e32 v104, 0xbfb8aa3b, v96
	v_mul_f32_e32 v105, 0xbfb8aa3b, v97
	v_mul_f32_e32 v106, 0xbfb8aa3b, v98
	v_mul_f32_e32 v107, 0xbfb8aa3b, v99
	v_exp_f32_e32 v104, v104
	v_exp_f32_e32 v105, v105
	v_exp_f32_e32 v106, v106
	v_exp_f32_e32 v107, v107
	v_add_f32_e32 v104, 1.0, v104
	v_add_f32_e32 v105, 1.0, v105
	v_add_f32_e32 v106, 1.0, v106
	v_add_f32_e32 v107, 1.0, v107
	v_div_scale_f32 v108, s[0:1], v104, v104, v96
	v_div_scale_f32 v109, s[0:1], v105, v105, v97
	v_div_scale_f32 v110, s[0:1], v106, v106, v98
	v_div_scale_f32 v111, s[0:1], v107, v107, v99
	v_rcp_f32_e32 v112, v108
	v_rcp_f32_e32 v113, v109
	v_rcp_f32_e32 v114, v110
	v_rcp_f32_e32 v115, v111
	v_fma_f32 v100, -v108, v112, 1.0
	v_fma_f32 v101, -v109, v113, 1.0
	v_fma_f32 v102, -v110, v114, 1.0
	v_fma_f32 v103, -v111, v115, 1.0
	v_fmac_f32_e32 v112, v100, v112
	v_fmac_f32_e32 v113, v101, v113
	v_fmac_f32_e32 v114, v102, v114
	v_fmac_f32_e32 v115, v103, v115
	v_div_scale_f32 v116, vcc, v96, v104, v96
	v_mul_f32_e32 v100, v116, v112
	v_fma_f32 v120, -v108, v100, v116
	v_fmac_f32_e32 v100, v120, v112
	v_fma_f32 v120, -v108, v100, v116
	v_div_fmas_f32 v120, v120, v112, v100
	v_div_fixup_f32 v100, v120, v104, v96
	v_div_scale_f32 v117, vcc, v97, v105, v97
	v_mul_f32_e32 v101, v117, v113
	v_fma_f32 v120, -v109, v101, v117
	v_fmac_f32_e32 v101, v120, v113
	v_fma_f32 v120, -v109, v101, v117
	v_div_fmas_f32 v120, v120, v113, v101
	v_div_fixup_f32 v101, v120, v105, v97
	v_div_scale_f32 v118, vcc, v98, v106, v98
	v_mul_f32_e32 v102, v118, v114
	v_fma_f32 v120, -v110, v102, v118
	v_fmac_f32_e32 v102, v120, v114
	v_fma_f32 v120, -v110, v102, v118
	v_div_fmas_f32 v120, v120, v114, v102
	v_div_fixup_f32 v102, v120, v106, v98
	v_div_scale_f32 v119, vcc, v99, v107, v99
	v_mul_f32_e32 v103, v119, v115
	v_fma_f32 v120, -v111, v103, v119
	v_fmac_f32_e32 v103, v120, v115
	v_fma_f32 v120, -v111, v103, v119
	v_div_fmas_f32 v120, v120, v115, v103
	v_div_fixup_f32 v103, v120, v107, v99
	s_waitcnt lgkmcnt(0)
; __device__ __forceinline__ float bflo(unsigned w) { return __uint_as_float(w << 16); }
; __device__ __forceinline__ float bfhi(unsigned w) { return __uint_as_float(w & 0xffff0000u); }
; __device__ __forceinline__ float silu_f(float x) { return x / (1.0f + __expf(-x)); }
; __device__ void da_unit(char* lds, const Params& p, int layer, int unit) {
;     ...
;         for (int k = 0; k < 4; ++k)
; #pragma unroll
;             for (int g = 0; g < 4; ++g) {
;                 const int d0 = 32 * k + 8 * g + 4 * h2;
;                 const f32x4 gg = *(const f32x4*)(sg + d0);
;                 const u32x2 gw = gwv[k * 4 + g];
;                 const float o0 = O[k][4 * g + 0] * rstd * gg[0] * silu_f(bflo(gw.x));
;                 const float o1 = O[k][4 * g + 1] * rstd * gg[1] * silu_f(bfhi(gw.x));
;                 const float o2 = O[k][4 * g + 2] * rstd * gg[2] * silu_f(bflo(gw.y));
;                 const float o3 = O[k][4 * g + 3] * rstd * gg[3] * silu_f(bfhi(gw.y));
;                 u32x2 w; w.x = cvt_pk_bf16(o0, o1); w.y = cvt_pk_bf16(o2, o3);
;                 *(u32x2*)(p.o + tokq * 1024 + h * 128 + d0) = w;
	v_mul_f32_e32 v28, v28, v70
	v_mul_f32_e32 v28, v28, v216
	v_mul_f32_e32 v28, v28, v100
	v_mul_f32_e32 v29, v29, v70
	v_mul_f32_e32 v29, v29, v217
	v_mul_f32_e32 v29, v29, v101
	v_mul_f32_e32 v30, v30, v70
	v_mul_f32_e32 v30, v30, v218
	v_mul_f32_e32 v30, v30, v102
	v_mul_f32_e32 v31, v31, v70
	v_mul_f32_e32 v31, v31, v219
	v_mul_f32_e32 v31, v31, v103
	v_cvt_pk_bf16_f32 v96, v28, v29
	v_cvt_pk_bf16_f32 v97, v30, v31
	global_store_dwordx2 v[78:79], v[96:97], off offset:48
	ds_read_b128 v[216:219], v72 offset:384
	v_lshlrev_b32_e32 v96, 16, v208
	v_and_b32_e32 v97, 0xffff0000, v208
	v_lshlrev_b32_e32 v98, 16, v209
	v_and_b32_e32 v99, 0xffff0000, v209
	v_mul_f32_e32 v104, 0xbfb8aa3b, v96
	v_mul_f32_e32 v105, 0xbfb8aa3b, v97
	v_mul_f32_e32 v106, 0xbfb8aa3b, v98
	v_mul_f32_e32 v107, 0xbfb8aa3b, v99
	v_exp_f32_e32 v104, v104
	v_exp_f32_e32 v105, v105
	v_exp_f32_e32 v106, v106
	v_exp_f32_e32 v107, v107
	v_add_f32_e32 v104, 1.0, v104
	v_add_f32_e32 v105, 1.0, v105
	v_add_f32_e32 v106, 1.0, v106
	v_add_f32_e32 v107, 1.0, v107
	v_div_scale_f32 v108, s[0:1], v104, v104, v96
	v_div_scale_f32 v109, s[0:1], v105, v105, v97
	v_div_scale_f32 v110, s[0:1], v106, v106, v98
	v_div_scale_f32 v111, s[0:1], v107, v107, v99
	v_rcp_f32_e32 v112, v108
	v_rcp_f32_e32 v113, v109
	v_rcp_f32_e32 v114, v110
	v_rcp_f32_e32 v115, v111
	v_fma_f32 v100, -v108, v112, 1.0
	v_fma_f32 v101, -v109, v113, 1.0
	v_fma_f32 v102, -v110, v114, 1.0
	v_fma_f32 v103, -v111, v115, 1.0
	v_fmac_f32_e32 v112, v100, v112
	v_fmac_f32_e32 v113, v101, v113
	v_fmac_f32_e32 v114, v102, v114
	v_fmac_f32_e32 v115, v103, v115
	v_div_scale_f32 v116, vcc, v96, v104, v96
	v_mul_f32_e32 v100, v116, v112
	v_fma_f32 v120, -v108, v100, v116
	v_fmac_f32_e32 v100, v120, v112
	v_fma_f32 v120, -v108, v100, v116
	v_div_fmas_f32 v120, v120, v112, v100
	v_div_fixup_f32 v100, v120, v104, v96
	v_div_scale_f32 v117, vcc, v97, v105, v97
	v_mul_f32_e32 v101, v117, v113
	v_fma_f32 v120, -v109, v101, v117
	v_fmac_f32_e32 v101, v120, v113
	v_fma_f32 v120, -v109, v101, v117
	v_div_fmas_f32 v120, v120, v113, v101
	v_div_fixup_f32 v101, v120, v105, v97
	v_div_scale_f32 v118, vcc, v98, v106, v98
	v_mul_f32_e32 v102, v118, v114
	v_fma_f32 v120, -v110, v102, v118
	v_fmac_f32_e32 v102, v120, v114
	v_fma_f32 v120, -v110, v102, v118
	v_div_fmas_f32 v120, v120, v114, v102
	v_div_fixup_f32 v102, v120, v106, v98
	v_div_scale_f32 v119, vcc, v99, v107, v99
	v_mul_f32_e32 v103, v119, v115
	v_fma_f32 v120, -v111, v103, v119
	v_fmac_f32_e32 v103, v120, v115
	v_fma_f32 v120, -v111, v103, v119
	v_div_fmas_f32 v120, v120, v115, v103
	v_div_fixup_f32 v103, v120, v107, v99
	s_waitcnt lgkmcnt(0)
	v_mul_f32_e32 v0, v0, v70
	v_mul_f32_e32 v0, v0, v216
	v_mul_f32_e32 v0, v0, v100
	v_mul_f32_e32 v1, v1, v70
	v_mul_f32_e32 v1, v1, v217
	v_mul_f32_e32 v1, v1, v101
	v_mul_f32_e32 v2, v2, v70
	v_mul_f32_e32 v2, v2, v218
	v_mul_f32_e32 v2, v2, v102
	v_mul_f32_e32 v3, v3, v70
	v_mul_f32_e32 v3, v3, v219
	v_mul_f32_e32 v3, v3, v103
	v_cvt_pk_bf16_f32 v96, v0, v1
	v_cvt_pk_bf16_f32 v97, v2, v3
	global_store_dwordx2 v[78:79], v[96:97], off offset:64
	ds_read_b128 v[216:219], v72 offset:416
	v_lshlrev_b32_e32 v96, 16, v210
	v_and_b32_e32 v97, 0xffff0000, v210
	v_lshlrev_b32_e32 v98, 16, v211
	v_and_b32_e32 v99, 0xffff0000, v211
	v_mul_f32_e32 v104, 0xbfb8aa3b, v96
	v_mul_f32_e32 v105, 0xbfb8aa3b, v97
	v_mul_f32_e32 v106, 0xbfb8aa3b, v98
	v_mul_f32_e32 v107, 0xbfb8aa3b, v99
	v_exp_f32_e32 v104, v104
	v_exp_f32_e32 v105, v105
	v_exp_f32_e32 v106, v106
	v_exp_f32_e32 v107, v107
	v_add_f32_e32 v104, 1.0, v104
	v_add_f32_e32 v105, 1.0, v105
	v_add_f32_e32 v106, 1.0, v106
	v_add_f32_e32 v107, 1.0, v107
	v_div_scale_f32 v108, s[0:1], v104, v104, v96
	v_div_scale_f32 v109, s[0:1], v105, v105, v97
	v_div_scale_f32 v110, s[0:1], v106, v106, v98
	v_div_scale_f32 v111, s[0:1], v107, v107, v99
	v_rcp_f32_e32 v112, v108
	v_rcp_f32_e32 v113, v109
	v_rcp_f32_e32 v114, v110
	v_rcp_f32_e32 v115, v111
	v_fma_f32 v100, -v108, v112, 1.0
	v_fma_f32 v101, -v109, v113, 1.0
	v_fma_f32 v102, -v110, v114, 1.0
	v_fma_f32 v103, -v111, v115, 1.0
	v_fmac_f32_e32 v112, v100, v112
	v_fmac_f32_e32 v113, v101, v113
	v_fmac_f32_e32 v114, v102, v114
	v_fmac_f32_e32 v115, v103, v115
	v_div_scale_f32 v116, vcc, v96, v104, v96
	v_mul_f32_e32 v100, v116, v112
	v_fma_f32 v120, -v108, v100, v116
	v_fmac_f32_e32 v100, v120, v112
	v_fma_f32 v120, -v108, v100, v116
	v_div_fmas_f32 v120, v120, v112, v100
	v_div_fixup_f32 v100, v120, v104, v96
	v_div_scale_f32 v117, vcc, v97, v105, v97
	v_mul_f32_e32 v101, v117, v113
	v_fma_f32 v120, -v109, v101, v117
	v_fmac_f32_e32 v101, v120, v113
	v_fma_f32 v120, -v109, v101, v117
	v_div_fmas_f32 v120, v120, v113, v101
	v_div_fixup_f32 v101, v120, v105, v97
	v_div_scale_f32 v118, vcc, v98, v106, v98
	v_mul_f32_e32 v102, v118, v114
	v_fma_f32 v120, -v110, v102, v118
	v_fmac_f32_e32 v102, v120, v114
	v_fma_f32 v120, -v110, v102, v118
	v_div_fmas_f32 v120, v120, v114, v102
	v_div_fixup_f32 v102, v120, v106, v98
	v_div_scale_f32 v119, vcc, v99, v107, v99
	v_mul_f32_e32 v103, v119, v115
	v_fma_f32 v120, -v111, v103, v119
	v_fmac_f32_e32 v103, v120, v115
	v_fma_f32 v120, -v111, v103, v119
	v_div_fmas_f32 v120, v120, v115, v103
	v_div_fixup_f32 v103, v120, v107, v99
	s_waitcnt lgkmcnt(0)
; __device__ __forceinline__ float bflo(unsigned w) { return __uint_as_float(w << 16); }
; __device__ __forceinline__ float bfhi(unsigned w) { return __uint_as_float(w & 0xffff0000u); }
; __device__ __forceinline__ float silu_f(float x) { return x / (1.0f + __expf(-x)); }
; __device__ void da_unit(char* lds, const Params& p, int layer, int unit) {
;     ...
;         for (int k = 0; k < 4; ++k)
; #pragma unroll
;             for (int g = 0; g < 4; ++g) {
;                 const int d0 = 32 * k + 8 * g + 4 * h2;
;                 const f32x4 gg = *(const f32x4*)(sg + d0);
;                 const u32x2 gw = gwv[k * 4 + g];
;                 const float o0 = O[k][4 * g + 0] * rstd * gg[0] * silu_f(bflo(gw.x));
;                 const float o1 = O[k][4 * g + 1] * rstd * gg[1] * silu_f(bfhi(gw.x));
;                 const float o2 = O[k][4 * g + 2] * rstd * gg[2] * silu_f(bflo(gw.y));
;                 const float o3 = O[k][4 * g + 3] * rstd * gg[3] * silu_f(bfhi(gw.y));
;                 u32x2 w; w.x = cvt_pk_bf16(o0, o1); w.y = cvt_pk_bf16(o2, o3);
;                 *(u32x2*)(p.o + tokq * 1024 + h * 128 + d0) = w;
	v_mul_f32_e32 v4, v4, v70
	v_mul_f32_e32 v4, v4, v216
	v_mul_f32_e32 v4, v4, v100
	v_mul_f32_e32 v5, v5, v70
	v_mul_f32_e32 v5, v5, v217
	v_mul_f32_e32 v5, v5, v101
	v_mul_f32_e32 v6, v6, v70
	v_mul_f32_e32 v6, v6, v218
	v_mul_f32_e32 v6, v6, v102
	v_mul_f32_e32 v7, v7, v70
	v_mul_f32_e32 v7, v7, v219
	v_mul_f32_e32 v7, v7, v103
	v_cvt_pk_bf16_f32 v96, v4, v5
	v_cvt_pk_bf16_f32 v97, v6, v7
	global_store_dwordx2 v[78:79], v[96:97], off offset:80
	ds_read_b128 v[216:219], v72 offset:448
	v_lshlrev_b32_e32 v96, 16, v212
	v_and_b32_e32 v97, 0xffff0000, v212
	v_lshlrev_b32_e32 v98, 16, v213
	v_and_b32_e32 v99, 0xffff0000, v213
	v_mul_f32_e32 v104, 0xbfb8aa3b, v96
	v_mul_f32_e32 v105, 0xbfb8aa3b, v97
	v_mul_f32_e32 v106, 0xbfb8aa3b, v98
	v_mul_f32_e32 v107, 0xbfb8aa3b, v99
	v_exp_f32_e32 v104, v104
	v_exp_f32_e32 v105, v105
	v_exp_f32_e32 v106, v106
	v_exp_f32_e32 v107, v107
	v_add_f32_e32 v104, 1.0, v104
	v_add_f32_e32 v105, 1.0, v105
	v_add_f32_e32 v106, 1.0, v106
	v_add_f32_e32 v107, 1.0, v107
	v_div_scale_f32 v108, s[0:1], v104, v104, v96
	v_div_scale_f32 v109, s[0:1], v105, v105, v97
	v_div_scale_f32 v110, s[0:1], v106, v106, v98
	v_div_scale_f32 v111, s[0:1], v107, v107, v99
	v_rcp_f32_e32 v112, v108
	v_rcp_f32_e32 v113, v109
	v_rcp_f32_e32 v114, v110
	v_rcp_f32_e32 v115, v111
	v_fma_f32 v100, -v108, v112, 1.0
	v_fma_f32 v101, -v109, v113, 1.0
	v_fma_f32 v102, -v110, v114, 1.0
	v_fma_f32 v103, -v111, v115, 1.0
	v_fmac_f32_e32 v112, v100, v112
	v_fmac_f32_e32 v113, v101, v113
	v_fmac_f32_e32 v114, v102, v114
	v_fmac_f32_e32 v115, v103, v115
	v_div_scale_f32 v116, vcc, v96, v104, v96
	v_mul_f32_e32 v100, v116, v112
	v_fma_f32 v120, -v108, v100, v116
	v_fmac_f32_e32 v100, v120, v112
	v_fma_f32 v120, -v108, v100, v116
	v_div_fmas_f32 v120, v120, v112, v100
	v_div_fixup_f32 v100, v120, v104, v96
	v_div_scale_f32 v117, vcc, v97, v105, v97
	v_mul_f32_e32 v101, v117, v113
	v_fma_f32 v120, -v109, v101, v117
	v_fmac_f32_e32 v101, v120, v113
	v_fma_f32 v120, -v109, v101, v117
	v_div_fmas_f32 v120, v120, v113, v101
	v_div_fixup_f32 v101, v120, v105, v97
	v_div_scale_f32 v118, vcc, v98, v106, v98
	v_mul_f32_e32 v102, v118, v114
	v_fma_f32 v120, -v110, v102, v118
	v_fmac_f32_e32 v102, v120, v114
	v_fma_f32 v120, -v110, v102, v118
	v_div_fmas_f32 v120, v120, v114, v102
	v_div_fixup_f32 v102, v120, v106, v98
	v_div_scale_f32 v119, vcc, v99, v107, v99
	v_mul_f32_e32 v103, v119, v115
	v_fma_f32 v120, -v111, v103, v119
	v_fmac_f32_e32 v103, v120, v115
	v_fma_f32 v120, -v111, v103, v119
	v_div_fmas_f32 v120, v120, v115, v103
	v_div_fixup_f32 v103, v120, v107, v99
	s_waitcnt lgkmcnt(0)
	v_mul_f32_e32 v8, v8, v70
	v_mul_f32_e32 v8, v8, v216
	v_mul_f32_e32 v8, v8, v100
	v_mul_f32_e32 v9, v9, v70
	v_mul_f32_e32 v9, v9, v217
	v_mul_f32_e32 v9, v9, v101
	v_mul_f32_e32 v10, v10, v70
	v_mul_f32_e32 v10, v10, v218
	v_mul_f32_e32 v10, v10, v102
	v_mul_f32_e32 v11, v11, v70
	v_mul_f32_e32 v11, v11, v219
	v_mul_f32_e32 v11, v11, v103
	v_cvt_pk_bf16_f32 v96, v8, v9
	v_cvt_pk_bf16_f32 v97, v10, v11
	global_store_dwordx2 v[78:79], v[96:97], off offset:96
	ds_read_b128 v[216:219], v72 offset:480
	v_lshlrev_b32_e32 v96, 16, v214
	v_and_b32_e32 v97, 0xffff0000, v214
	v_lshlrev_b32_e32 v98, 16, v215
	v_and_b32_e32 v99, 0xffff0000, v215
	v_mul_f32_e32 v104, 0xbfb8aa3b, v96
	v_mul_f32_e32 v105, 0xbfb8aa3b, v97
	v_mul_f32_e32 v106, 0xbfb8aa3b, v98
	v_mul_f32_e32 v107, 0xbfb8aa3b, v99
	v_exp_f32_e32 v104, v104
	v_exp_f32_e32 v105, v105
	v_exp_f32_e32 v106, v106
	v_exp_f32_e32 v107, v107
	v_add_f32_e32 v104, 1.0, v104
	v_add_f32_e32 v105, 1.0, v105
	v_add_f32_e32 v106, 1.0, v106
	v_add_f32_e32 v107, 1.0, v107
	v_div_scale_f32 v108, s[0:1], v104, v104, v96
	v_div_scale_f32 v109, s[0:1], v105, v105, v97
	v_div_scale_f32 v110, s[0:1], v106, v106, v98
	v_div_scale_f32 v111, s[0:1], v107, v107, v99
	v_rcp_f32_e32 v112, v108
	v_rcp_f32_e32 v113, v109
	v_rcp_f32_e32 v114, v110
	v_rcp_f32_e32 v115, v111
	v_fma_f32 v100, -v108, v112, 1.0
	v_fma_f32 v101, -v109, v113, 1.0
	v_fma_f32 v102, -v110, v114, 1.0
	v_fma_f32 v103, -v111, v115, 1.0
	v_fmac_f32_e32 v112, v100, v112
	v_fmac_f32_e32 v113, v101, v113
	v_fmac_f32_e32 v114, v102, v114
	v_fmac_f32_e32 v115, v103, v115
	v_div_scale_f32 v116, vcc, v96, v104, v96
	v_mul_f32_e32 v100, v116, v112
	v_fma_f32 v120, -v108, v100, v116
	v_fmac_f32_e32 v100, v120, v112
	v_fma_f32 v120, -v108, v100, v116
	v_div_fmas_f32 v120, v120, v112, v100
	v_div_fixup_f32 v100, v120, v104, v96
	v_div_scale_f32 v117, vcc, v97, v105, v97
	v_mul_f32_e32 v101, v117, v113
	v_fma_f32 v120, -v109, v101, v117
	v_fmac_f32_e32 v101, v120, v113
	v_fma_f32 v120, -v109, v101, v117
	v_div_fmas_f32 v120, v120, v113, v101
	v_div_fixup_f32 v101, v120, v105, v97
	v_div_scale_f32 v118, vcc, v98, v106, v98
	v_mul_f32_e32 v102, v118, v114
	v_fma_f32 v120, -v110, v102, v118
	v_fmac_f32_e32 v102, v120, v114
	v_fma_f32 v120, -v110, v102, v118
	v_div_fmas_f32 v120, v120, v114, v102
	v_div_fixup_f32 v102, v120, v106, v98
	v_div_scale_f32 v119, vcc, v99, v107, v99
	v_mul_f32_e32 v103, v119, v115
	v_fma_f32 v120, -v111, v103, v119
	v_fmac_f32_e32 v103, v120, v115
	v_fma_f32 v120, -v111, v103, v119
	v_div_fmas_f32 v120, v120, v115, v103
	v_div_fixup_f32 v103, v120, v107, v99
	s_waitcnt lgkmcnt(0)
	v_mul_f32_e32 v12, v12, v70
	v_mul_f32_e32 v12, v12, v216
	v_mul_f32_e32 v12, v12, v100
	v_mul_f32_e32 v13, v13, v70
	v_mul_f32_e32 v13, v13, v217
	v_mul_f32_e32 v13, v13, v101
	v_mul_f32_e32 v14, v14, v70
	v_mul_f32_e32 v14, v14, v218
	v_mul_f32_e32 v14, v14, v102
	v_mul_f32_e32 v15, v15, v70
	v_mul_f32_e32 v15, v15, v219
	v_mul_f32_e32 v15, v15, v103
	v_cvt_pk_bf16_f32 v96, v12, v13
	v_cvt_pk_bf16_f32 v97, v14, v15
	global_store_dwordx2 v[78:79], v[96:97], off offset:112
	s_branch .LBB0_450
